# hand-written P0c: S5 GEMM operand expansion built from LDS-staged tables with coalesced 16-byte stores (was one dependent global load + wait per element)
# speedup vs baseline: 1.0074x; 1.0074x over previous
.LBB0_377:
	s_and_b64 vcc, exec, s[0:1]
	s_cbranch_vccz .LBB0_582
	s_load_dwordx2 s[18:19], s[78:79], 0x100
	v_readfirstlane_b32 s31, v224
	s_lshr_b32 s31, s31, 6
	s_lshr_b32 s5, s2, 3
	s_lshr_b32 s28, s5, 4
	s_and_b32 s29, s5, 15
	s_and_b32 s30, s2, 7
	v_lshlrev_b32_e32 v0, 4, v224
	v_add_u32_e32 v1, 0x10000, v0
	v_and_b32_e32 v2, 63, v224
	v_lshlrev_b32_e32 v3, 4, v2
	s_mul_i32 s36, s28, 0x1c4000
	s_waitcnt lgkmcnt(0)
	s_add_u32 s20, s18, s36
	s_addc_u32 s21, s19, 0
	s_add_u32 s20, s20, 0x6040000
	s_addc_u32 s21, s21, 0
	s_lshl_b32 s36, s29, 16
	s_add_u32 s22, s20, s36
	s_addc_u32 s23, s21, 0
	s_add_u32 s22, s22, 0xc4000
	s_addc_u32 s23, s23, 0
	global_load_dwordx4 v[4:7], v0, s[22:23]
	s_add_u32 s22, s22, 0x2000
	s_addc_u32 s23, s23, 0
	global_load_dwordx4 v[8:11], v0, s[22:23]
	s_add_u32 s22, s22, 0x2000
	s_addc_u32 s23, s23, 0
	global_load_dwordx4 v[12:15], v0, s[22:23]
	s_add_u32 s22, s22, 0x2000
	s_addc_u32 s23, s23, 0
	global_load_dwordx4 v[16:19], v0, s[22:23]
	s_add_u32 s22, s22, 0x2000
	s_addc_u32 s23, s23, 0
	global_load_dwordx4 v[124:127], v0, s[22:23]
	s_add_u32 s22, s22, 0x2000
	s_addc_u32 s23, s23, 0
	global_load_dwordx4 v[128:131], v0, s[22:23]
	s_add_u32 s22, s22, 0x2000
	s_addc_u32 s23, s23, 0
	global_load_dwordx4 v[132:135], v0, s[22:23]
	s_add_u32 s22, s22, 0x2000
	s_addc_u32 s23, s23, 0
	global_load_dwordx4 v[136:139], v0, s[22:23]
	s_mul_i32 s36, s29, 0x8400
	s_add_u32 s22, s20, s36
	s_addc_u32 s23, s21, 0
	global_load_dwordx4 v[148:151], v0, s[22:23]
	s_add_u32 s22, s22, 0x2000
	s_addc_u32 s23, s23, 0
	global_load_dwordx4 v[152:155], v0, s[22:23]
	s_add_u32 s22, s22, 0x2000
	s_addc_u32 s23, s23, 0
	global_load_dwordx4 v[164:167], v0, s[22:23]
	s_add_u32 s22, s22, 0x2000
	s_addc_u32 s23, s23, 0
	global_load_dwordx4 v[168:171], v0, s[22:23]
	s_add_u32 s22, s22, 0x2000
	s_addc_u32 s23, s23, 0
	s_cmp_eq_u32 s31, 0
	s_cbranch_scc0 .Lp0c_a
	global_load_dwordx4 v[172:175], v0, s[22:23]
.Lp0c_a:
	s_lshl_b32 s36, s29, 14
	s_add_u32 s22, s20, s36
	s_addc_u32 s23, s21, 0
	s_add_u32 s22, s22, 0x84000
	s_addc_u32 s23, s23, 0
	global_load_dwordx4 v[176:179], v0, s[22:23]
	s_add_u32 s22, s22, 0x2000
	s_addc_u32 s23, s23, 0
	global_load_dwordx4 v[180:183], v0, s[22:23]
	s_cmp_lt_u32 s31, 4
	s_cselect_b32 s36, 0, 8
	s_cselect_b32 s41, 0, 0x1000
	s_add_u32 s36, s36, 0x70
	s_load_dwordx2 s[22:23], s[78:79], s36
	s_lshl_b32 s38, s5, 12
	s_waitcnt lgkmcnt(0)
	s_add_u32 s22, s22, s38
	s_addc_u32 s23, s23, 0
	s_sub_u32 s22, s22, s41
	s_subb_u32 s23, s23, 0
	global_load_dwordx4 v[184:187], v0, s[22:23]
	s_load_dwordx2 s[22:23], s[78:79], 0x80
	s_lshl_b32 s38, s5, 6
	v_bfe_u32 v188, v224, 4, 4
	v_lshlrev_b32_e32 v189, 2, v188
	s_waitcnt lgkmcnt(0)
	s_add_u32 s22, s22, s38
	s_addc_u32 s23, s23, 0
	global_load_dword v190, v189, s[22:23]
	s_waitcnt vmcnt(0)
	ds_write_b128 v0, v[4:7]
	ds_write_b128 v0, v[8:11] offset:8192
	ds_write_b128 v0, v[12:15] offset:16384
	ds_write_b128 v0, v[16:19] offset:24576
	ds_write_b128 v0, v[124:127] offset:32768
	ds_write_b128 v0, v[128:131] offset:40960
	ds_write_b128 v0, v[132:135] offset:49152
	ds_write_b128 v0, v[136:139] offset:57344
	ds_write_b128 v1, v[148:151]
	ds_write_b128 v1, v[152:155] offset:8192
	ds_write_b128 v1, v[164:167] offset:16384
	ds_write_b128 v1, v[168:171] offset:24576
	s_cmp_eq_u32 s31, 0
	s_cbranch_scc0 .Lp0c_b
	ds_write_b128 v1, v[172:175] offset:32768
.Lp0c_b:
	ds_write_b128 v1, v[176:179] offset:33792
	ds_write_b128 v1, v[180:183] offset:41984
	ds_write_b128 v1, v[184:187] offset:50176
	s_cmp_lt_u32 s31, 4
	s_cbranch_scc0 .Lp0c_c
	v_and_b32_e32 v189, 15, v224
	v_cmp_eq_u32_e32 vcc, v189, v188
	v_cndmask_b32_e32 v190, 0, v190, vcc
	v_lshlrev_b32_e32 v189, 2, v224
	v_add_u32_e32 v189, 0x1e400, v189
	ds_write_b32 v189, v190
.Lp0c_c:
	s_waitcnt lgkmcnt(0)
	s_barrier
	s_lshl_b32 s0, s30, 2
	s_lshr_b32 s36, s31, 1
	s_add_u32 s0, s0, s36
	s_add_u32 s1, s0, 1
	s_sub_u32 s4, 32, s0
	v_mov_b32_e32 v140, s1
	v_mov_b32_e32 v142, s4
	s_lshl_b32 s36, s29, 9
	s_lshl_b32 s38, s30, 6
	s_add_u32 s36, s36, s38
	s_lshl_b32 s38, s31, 3
	s_add_u32 s36, s36, s38
	s_mul_i32 s36, s36, 0x600
	s_mul_i32 s38, s28, 0x3020000
	s_add_u32 s24, s18, s38
	s_addc_u32 s25, s19, 0
	s_add_u32 s26, s24, 0x2c20000
	s_addc_u32 s27, s25, 0
	s_add_u32 s24, s24, 0x2020000
	s_addc_u32 s25, s25, 0
	s_add_u32 s24, s24, s36
	s_addc_u32 s25, s25, 0
	s_and_b32 s41, s31, 1
	s_lshl_b32 s41, s41, 9
	v_mov_b32_e32 v122, v3
	s_mov_b64 exec, -1
	v_mov_b32_e32 v100, v2
	v_lshrrev_b32_e32 v102, 1, v100
	v_sub_u32_e32 v104, s0, v102
	v_max_i32_e32 v106, 0, v104
	v_sub_u32_e32 v108, 0, v104
	v_max_i32_e32 v108, 0, v108
	v_and_b32_e32 v118, 1, v100
	v_lshlrev_b32_e32 v118, 5, v118
	v_add_u32_e32 v118, s41, v118
	v_lshl_add_u32 v110, v106, 10, v118
	v_lshl_add_u32 v112, v108, 10, v118
	v_add_u32_e32 v112, 0x8000, v112
	v_add_u32_e32 v114, 0x1e400, v118
	ds_read_b128 v[12:15], v110
	ds_read_b128 v[16:19], v110 offset:16
	ds_read_b128 v[124:127], v112
	ds_read_b128 v[128:131], v112 offset:16
	ds_read_b128 v[132:135], v114
	ds_read_b128 v[136:139], v114 offset:16
	s_waitcnt lgkmcnt(0)
	v_cmp_le_i32_e32 vcc, 0, v104
	v_cndmask_b32_e32 v4, 0, v12, vcc
	v_cndmask_b32_e32 v5, 0, v13, vcc
	v_cndmask_b32_e32 v6, 0, v14, vcc
	v_cndmask_b32_e32 v7, 0, v15, vcc
	v_cndmask_b32_e32 v8, 0, v16, vcc
	v_cndmask_b32_e32 v9, 0, v17, vcc
	v_cndmask_b32_e32 v10, 0, v18, vcc
	v_cndmask_b32_e32 v11, 0, v19, vcc
	v_cmp_ge_i32_e32 vcc, 0, v104
	v_cndmask_b32_e32 v124, 0, v124, vcc
	v_cndmask_b32_e32 v125, 0, v125, vcc
	v_cndmask_b32_e32 v126, 0, v126, vcc
	v_cndmask_b32_e32 v127, 0, v127, vcc
	v_cndmask_b32_e32 v128, 0, v128, vcc
	v_cndmask_b32_e32 v129, 0, v129, vcc
	v_cndmask_b32_e32 v130, 0, v130, vcc
	v_cndmask_b32_e32 v131, 0, v131, vcc
	v_add_f32_e32 v4, v4, v124
	v_add_f32_e32 v5, v5, v125
	v_add_f32_e32 v6, v6, v126
	v_add_f32_e32 v7, v7, v127
	v_add_f32_e32 v8, v8, v128
	v_add_f32_e32 v9, v9, v129
	v_add_f32_e32 v10, v10, v130
	v_add_f32_e32 v11, v11, v131
	v_cmp_eq_u32_e32 vcc, 0, v104
	v_cndmask_b32_e32 v132, 0, v132, vcc
	v_cndmask_b32_e32 v133, 0, v133, vcc
	v_cndmask_b32_e32 v134, 0, v134, vcc
	v_cndmask_b32_e32 v135, 0, v135, vcc
	v_cndmask_b32_e32 v136, 0, v136, vcc
	v_cndmask_b32_e32 v137, 0, v137, vcc
	v_cndmask_b32_e32 v138, 0, v138, vcc
	v_cndmask_b32_e32 v139, 0, v139, vcc
	v_add_f32_e32 v4, v4, v132
	v_add_f32_e32 v5, v5, v133
	v_add_f32_e32 v6, v6, v134
	v_add_f32_e32 v7, v7, v135
	v_add_f32_e32 v8, v8, v136
	v_add_f32_e32 v9, v9, v137
	v_add_f32_e32 v10, v10, v138
	v_add_f32_e32 v11, v11, v139
	v_cvt_pk_bf16_f32 v166, v4, v5
	v_cvt_pk_bf16_f32 v167, v6, v7
	v_cvt_pk_bf16_f32 v168, v8, v9
	v_cvt_pk_bf16_f32 v169, v10, v11
	s_mov_b64 exec, -1
	global_store_dwordx4 v122, v[166:169], s[24:25]
	s_nop 1
	s_mov_b32 exec_lo, -1
	s_mov_b32 exec_hi, 0
	v_mov_b32_e32 v100, v2
	v_lshrrev_b32_e32 v102, 4, v100
	v_and_b32_e32 v118, 7, v100
	v_lshlrev_b32_e32 v118, 3, v118
	v_cmp_ne_u32_e32 vcc, 0, v102
	v_cndmask_b32_e32 v106, v140, v142, vcc
	v_lshl_add_u32 v120, v102, 6, v118
	v_mul_u32_u24_e32 v120, 0x108, v120
	v_lshl_add_u32 v110, v106, 3, v120
	v_add_u32_e32 v110, 0x10000, v110
	v_lshlrev_b32_e32 v112, 2, v118
	v_add_u32_e32 v112, s41, v112
	ds_read_b64 v[20:21], v110
	ds_read_b64 v[98:99], v110 offset:264
	ds_read_b64 v[116:117], v110 offset:528
	ds_read_b64 v[148:149], v110 offset:792
	ds_read_b64 v[150:151], v110 offset:1056
	ds_read_b64 v[152:153], v110 offset:1320
	ds_read_b64 v[154:155], v110 offset:1584
	ds_read_b64 v[164:165], v110 offset:1848
	v_lshlrev_b32_e32 v112, 2, v118
	s_lshl_b32 s36, s41, 2
	v_add_u32_e32 v112, s36, v112
	v_add_u32_e32 v112, 0x1c400, v112
	ds_read_b128 v[12:15], v112
	ds_read_b128 v[16:19], v112 offset:16
	ds_read_b128 v[124:127], v112 offset:4096
	ds_read_b128 v[128:131], v112 offset:4112
	v_bfe_u32 v108, v100, 3, 1
	s_waitcnt lgkmcnt(0)
	v_cmp_ne_u32_e32 vcc, 0, v108
	v_mul_f32_e32 v170, v12, v20
	v_mul_f32_e32 v171, v124, v21
	v_mul_f32_e32 v172, v12, v21
	v_mul_f32_e32 v173, v124, v20
	v_sub_f32_e32 v170, v170, v171
	v_add_f32_e32 v172, v172, v173
	v_xor_b32_e32 v172, 0x80000000, v172
	v_cndmask_b32_e32 v4, v170, v172, vcc
	v_mul_f32_e32 v170, v13, v98
	v_mul_f32_e32 v171, v125, v99
	v_mul_f32_e32 v172, v13, v99
	v_mul_f32_e32 v173, v125, v98
	v_sub_f32_e32 v170, v170, v171
	v_add_f32_e32 v172, v172, v173
	v_xor_b32_e32 v172, 0x80000000, v172
	v_cndmask_b32_e32 v5, v170, v172, vcc
	v_mul_f32_e32 v170, v14, v116
	v_mul_f32_e32 v171, v126, v117
	v_mul_f32_e32 v172, v14, v117
	v_mul_f32_e32 v173, v126, v116
	v_sub_f32_e32 v170, v170, v171
	v_add_f32_e32 v172, v172, v173
	v_xor_b32_e32 v172, 0x80000000, v172
	v_cndmask_b32_e32 v6, v170, v172, vcc
	v_mul_f32_e32 v170, v15, v148
	v_mul_f32_e32 v171, v127, v149
	v_mul_f32_e32 v172, v15, v149
	v_mul_f32_e32 v173, v127, v148
	v_sub_f32_e32 v170, v170, v171
	v_add_f32_e32 v172, v172, v173
	v_xor_b32_e32 v172, 0x80000000, v172
	v_cndmask_b32_e32 v7, v170, v172, vcc
	v_mul_f32_e32 v170, v16, v150
	v_mul_f32_e32 v171, v128, v151
	v_mul_f32_e32 v172, v16, v151
	v_mul_f32_e32 v173, v128, v150
	v_sub_f32_e32 v170, v170, v171
	v_add_f32_e32 v172, v172, v173
	v_xor_b32_e32 v172, 0x80000000, v172
	v_cndmask_b32_e32 v8, v170, v172, vcc
	v_mul_f32_e32 v170, v17, v152
	v_mul_f32_e32 v171, v129, v153
	v_mul_f32_e32 v172, v17, v153
	v_mul_f32_e32 v173, v129, v152
	v_sub_f32_e32 v170, v170, v171
	v_add_f32_e32 v172, v172, v173
	v_xor_b32_e32 v172, 0x80000000, v172
	v_cndmask_b32_e32 v9, v170, v172, vcc
	v_mul_f32_e32 v170, v18, v154
	v_mul_f32_e32 v171, v130, v155
	v_mul_f32_e32 v172, v18, v155
	v_mul_f32_e32 v173, v130, v154
	v_sub_f32_e32 v170, v170, v171
	v_add_f32_e32 v172, v172, v173
	v_xor_b32_e32 v172, 0x80000000, v172
	v_cndmask_b32_e32 v10, v170, v172, vcc
	v_mul_f32_e32 v170, v19, v164
	v_mul_f32_e32 v171, v131, v165
	v_mul_f32_e32 v172, v19, v165
	v_mul_f32_e32 v173, v131, v164
	v_sub_f32_e32 v170, v170, v171
	v_add_f32_e32 v172, v172, v173
	v_xor_b32_e32 v172, 0x80000000, v172
	v_cndmask_b32_e32 v11, v170, v172, vcc
	v_cvt_pk_bf16_f32 v166, v4, v5
	v_cvt_pk_bf16_f32 v167, v6, v7
	v_cvt_pk_bf16_f32 v168, v8, v9
	v_cvt_pk_bf16_f32 v169, v10, v11
	s_mov_b32 exec_lo, 0
	s_mov_b32 exec_hi, -1
	v_add_u32_e32 v100, 0xffffffe0, v2
	v_lshrrev_b32_e32 v102, 1, v100
	v_sub_u32_e32 v104, s0, v102
	v_max_i32_e32 v106, 0, v104
	v_sub_u32_e32 v108, 0, v104
	v_max_i32_e32 v108, 0, v108
	v_and_b32_e32 v118, 1, v100
	v_lshlrev_b32_e32 v118, 5, v118
	v_add_u32_e32 v118, s41, v118
	v_add_u32_e32 v118, 0x40, v118
	v_lshl_add_u32 v110, v106, 10, v118
	v_lshl_add_u32 v112, v108, 10, v118
	v_add_u32_e32 v112, 0x8000, v112
	v_add_u32_e32 v114, 0x1e400, v118
	ds_read_b128 v[12:15], v110
	ds_read_b128 v[16:19], v110 offset:16
	ds_read_b128 v[124:127], v112
	ds_read_b128 v[128:131], v112 offset:16
	ds_read_b128 v[132:135], v114
	ds_read_b128 v[136:139], v114 offset:16
	s_waitcnt lgkmcnt(0)
	v_cmp_le_i32_e32 vcc, 0, v104
	v_cndmask_b32_e32 v4, 0, v12, vcc
	v_cndmask_b32_e32 v5, 0, v13, vcc
	v_cndmask_b32_e32 v6, 0, v14, vcc
	v_cndmask_b32_e32 v7, 0, v15, vcc
	v_cndmask_b32_e32 v8, 0, v16, vcc
	v_cndmask_b32_e32 v9, 0, v17, vcc
	v_cndmask_b32_e32 v10, 0, v18, vcc
	v_cndmask_b32_e32 v11, 0, v19, vcc
	v_cmp_ge_i32_e32 vcc, 0, v104
	v_cndmask_b32_e32 v124, 0, v124, vcc
	v_cndmask_b32_e32 v125, 0, v125, vcc
	v_cndmask_b32_e32 v126, 0, v126, vcc
	v_cndmask_b32_e32 v127, 0, v127, vcc
	v_cndmask_b32_e32 v128, 0, v128, vcc
	v_cndmask_b32_e32 v129, 0, v129, vcc
	v_cndmask_b32_e32 v130, 0, v130, vcc
	v_cndmask_b32_e32 v131, 0, v131, vcc
	v_add_f32_e32 v4, v4, v124
	v_add_f32_e32 v5, v5, v125
	v_add_f32_e32 v6, v6, v126
	v_add_f32_e32 v7, v7, v127
	v_add_f32_e32 v8, v8, v128
	v_add_f32_e32 v9, v9, v129
	v_add_f32_e32 v10, v10, v130
	v_add_f32_e32 v11, v11, v131
	v_cmp_eq_u32_e32 vcc, 0, v104
	v_cndmask_b32_e32 v132, 0, v132, vcc
	v_cndmask_b32_e32 v133, 0, v133, vcc
	v_cndmask_b32_e32 v134, 0, v134, vcc
	v_cndmask_b32_e32 v135, 0, v135, vcc
	v_cndmask_b32_e32 v136, 0, v136, vcc
	v_cndmask_b32_e32 v137, 0, v137, vcc
	v_cndmask_b32_e32 v138, 0, v138, vcc
	v_cndmask_b32_e32 v139, 0, v139, vcc
	v_add_f32_e32 v4, v4, v132
	v_add_f32_e32 v5, v5, v133
	v_add_f32_e32 v6, v6, v134
	v_add_f32_e32 v7, v7, v135
	v_add_f32_e32 v8, v8, v136
	v_add_f32_e32 v9, v9, v137
	v_add_f32_e32 v10, v10, v138
	v_add_f32_e32 v11, v11, v139
	v_cvt_pk_bf16_f32 v166, v4, v5
	v_cvt_pk_bf16_f32 v167, v6, v7
	v_cvt_pk_bf16_f32 v168, v8, v9
	v_cvt_pk_bf16_f32 v169, v10, v11
	s_mov_b64 exec, -1
	global_store_dwordx4 v122, v[166:169], s[24:25] offset:1024
	s_nop 1
	s_mov_b32 exec_lo, -1
	s_mov_b32 exec_hi, 0
	v_add_u32_e32 v100, 32, v2
	v_lshrrev_b32_e32 v102, 1, v100
	v_sub_u32_e32 v104, s0, v102
	v_max_i32_e32 v106, 0, v104
	v_sub_u32_e32 v108, 0, v104
	v_max_i32_e32 v108, 0, v108
	v_and_b32_e32 v118, 1, v100
	v_lshlrev_b32_e32 v118, 5, v118
	v_add_u32_e32 v118, s41, v118
	v_add_u32_e32 v118, 0x40, v118
	v_lshl_add_u32 v110, v106, 10, v118
	v_lshl_add_u32 v112, v108, 10, v118
	v_add_u32_e32 v112, 0x8000, v112
	v_add_u32_e32 v114, 0x1e400, v118
	ds_read_b128 v[12:15], v110
	ds_read_b128 v[16:19], v110 offset:16
	ds_read_b128 v[124:127], v112
	ds_read_b128 v[128:131], v112 offset:16
	ds_read_b128 v[132:135], v114
	ds_read_b128 v[136:139], v114 offset:16
	s_waitcnt lgkmcnt(0)
	v_cmp_le_i32_e32 vcc, 0, v104
	v_cndmask_b32_e32 v4, 0, v12, vcc
	v_cndmask_b32_e32 v5, 0, v13, vcc
	v_cndmask_b32_e32 v6, 0, v14, vcc
	v_cndmask_b32_e32 v7, 0, v15, vcc
	v_cndmask_b32_e32 v8, 0, v16, vcc
	v_cndmask_b32_e32 v9, 0, v17, vcc
	v_cndmask_b32_e32 v10, 0, v18, vcc
	v_cndmask_b32_e32 v11, 0, v19, vcc
	v_cmp_ge_i32_e32 vcc, 0, v104
	v_cndmask_b32_e32 v124, 0, v124, vcc
	v_cndmask_b32_e32 v125, 0, v125, vcc
	v_cndmask_b32_e32 v126, 0, v126, vcc
	v_cndmask_b32_e32 v127, 0, v127, vcc
	v_cndmask_b32_e32 v128, 0, v128, vcc
	v_cndmask_b32_e32 v129, 0, v129, vcc
	v_cndmask_b32_e32 v130, 0, v130, vcc
	v_cndmask_b32_e32 v131, 0, v131, vcc
	v_add_f32_e32 v4, v4, v124
	v_add_f32_e32 v5, v5, v125
	v_add_f32_e32 v6, v6, v126
	v_add_f32_e32 v7, v7, v127
	v_add_f32_e32 v8, v8, v128
	v_add_f32_e32 v9, v9, v129
	v_add_f32_e32 v10, v10, v130
	v_add_f32_e32 v11, v11, v131
	v_cmp_eq_u32_e32 vcc, 0, v104
	v_cndmask_b32_e32 v132, 0, v132, vcc
	v_cndmask_b32_e32 v133, 0, v133, vcc
	v_cndmask_b32_e32 v134, 0, v134, vcc
	v_cndmask_b32_e32 v135, 0, v135, vcc
	v_cndmask_b32_e32 v136, 0, v136, vcc
	v_cndmask_b32_e32 v137, 0, v137, vcc
	v_cndmask_b32_e32 v138, 0, v138, vcc
	v_cndmask_b32_e32 v139, 0, v139, vcc
	v_add_f32_e32 v4, v4, v132
	v_add_f32_e32 v5, v5, v133
	v_add_f32_e32 v6, v6, v134
	v_add_f32_e32 v7, v7, v135
	v_add_f32_e32 v8, v8, v136
	v_add_f32_e32 v9, v9, v137
	v_add_f32_e32 v10, v10, v138
	v_add_f32_e32 v11, v11, v139
	v_cvt_pk_bf16_f32 v166, v4, v5
	v_cvt_pk_bf16_f32 v167, v6, v7
	v_cvt_pk_bf16_f32 v168, v8, v9
	v_cvt_pk_bf16_f32 v169, v10, v11
	s_mov_b32 exec_lo, 0
	s_mov_b32 exec_hi, -1
	v_subrev_u32_e32 v100, 32, v2
	v_lshrrev_b32_e32 v102, 4, v100
	v_and_b32_e32 v118, 7, v100
	v_lshlrev_b32_e32 v118, 3, v118
	v_cmp_ne_u32_e32 vcc, 0, v102
	v_cndmask_b32_e32 v106, v140, v142, vcc
	v_lshl_add_u32 v120, v102, 6, v118
	v_mul_u32_u24_e32 v120, 0x108, v120
	v_lshl_add_u32 v110, v106, 3, v120
	v_add_u32_e32 v110, 0x10000, v110
	v_lshlrev_b32_e32 v112, 2, v118
	v_add_u32_e32 v112, s41, v112
	ds_read_b64 v[20:21], v110
	ds_read_b64 v[98:99], v110 offset:264
	ds_read_b64 v[116:117], v110 offset:528
	ds_read_b64 v[148:149], v110 offset:792
	ds_read_b64 v[150:151], v110 offset:1056
	ds_read_b64 v[152:153], v110 offset:1320
	ds_read_b64 v[154:155], v110 offset:1584
	ds_read_b64 v[164:165], v110 offset:1848
	v_lshlrev_b32_e32 v112, 2, v118
	s_lshl_b32 s36, s41, 2
	v_add_u32_e32 v112, s36, v112
	v_add_u32_e32 v112, 0x1c500, v112
	ds_read_b128 v[12:15], v112
	ds_read_b128 v[16:19], v112 offset:16
	ds_read_b128 v[124:127], v112 offset:4096
	ds_read_b128 v[128:131], v112 offset:4112
	v_bfe_u32 v108, v100, 3, 1
	s_waitcnt lgkmcnt(0)
	v_cmp_ne_u32_e32 vcc, 0, v108
	v_mul_f32_e32 v170, v12, v20
	v_mul_f32_e32 v171, v124, v21
	v_mul_f32_e32 v172, v12, v21
	v_mul_f32_e32 v173, v124, v20
	v_sub_f32_e32 v170, v170, v171
	v_add_f32_e32 v172, v172, v173
	v_xor_b32_e32 v172, 0x80000000, v172
	v_cndmask_b32_e32 v4, v170, v172, vcc
	v_mul_f32_e32 v170, v13, v98
	v_mul_f32_e32 v171, v125, v99
	v_mul_f32_e32 v172, v13, v99
	v_mul_f32_e32 v173, v125, v98
	v_sub_f32_e32 v170, v170, v171
	v_add_f32_e32 v172, v172, v173
	v_xor_b32_e32 v172, 0x80000000, v172
	v_cndmask_b32_e32 v5, v170, v172, vcc
	v_mul_f32_e32 v170, v14, v116
	v_mul_f32_e32 v171, v126, v117
	v_mul_f32_e32 v172, v14, v117
	v_mul_f32_e32 v173, v126, v116
	v_sub_f32_e32 v170, v170, v171
	v_add_f32_e32 v172, v172, v173
	v_xor_b32_e32 v172, 0x80000000, v172
	v_cndmask_b32_e32 v6, v170, v172, vcc
	v_mul_f32_e32 v170, v15, v148
	v_mul_f32_e32 v171, v127, v149
	v_mul_f32_e32 v172, v15, v149
	v_mul_f32_e32 v173, v127, v148
	v_sub_f32_e32 v170, v170, v171
	v_add_f32_e32 v172, v172, v173
	v_xor_b32_e32 v172, 0x80000000, v172
	v_cndmask_b32_e32 v7, v170, v172, vcc
	v_mul_f32_e32 v170, v16, v150
	v_mul_f32_e32 v171, v128, v151
	v_mul_f32_e32 v172, v16, v151
	v_mul_f32_e32 v173, v128, v150
	v_sub_f32_e32 v170, v170, v171
	v_add_f32_e32 v172, v172, v173
	v_xor_b32_e32 v172, 0x80000000, v172
	v_cndmask_b32_e32 v8, v170, v172, vcc
	v_mul_f32_e32 v170, v17, v152
	v_mul_f32_e32 v171, v129, v153
	v_mul_f32_e32 v172, v17, v153
	v_mul_f32_e32 v173, v129, v152
	v_sub_f32_e32 v170, v170, v171
	v_add_f32_e32 v172, v172, v173
	v_xor_b32_e32 v172, 0x80000000, v172
	v_cndmask_b32_e32 v9, v170, v172, vcc
	v_mul_f32_e32 v170, v18, v154
	v_mul_f32_e32 v171, v130, v155
	v_mul_f32_e32 v172, v18, v155
	v_mul_f32_e32 v173, v130, v154
	v_sub_f32_e32 v170, v170, v171
	v_add_f32_e32 v172, v172, v173
	v_xor_b32_e32 v172, 0x80000000, v172
	v_cndmask_b32_e32 v10, v170, v172, vcc
	v_mul_f32_e32 v170, v19, v164
	v_mul_f32_e32 v171, v131, v165
	v_mul_f32_e32 v172, v19, v165
	v_mul_f32_e32 v173, v131, v164
	v_sub_f32_e32 v170, v170, v171
	v_add_f32_e32 v172, v172, v173
	v_xor_b32_e32 v172, 0x80000000, v172
	v_cndmask_b32_e32 v11, v170, v172, vcc
	v_cvt_pk_bf16_f32 v166, v4, v5
	v_cvt_pk_bf16_f32 v167, v6, v7
	v_cvt_pk_bf16_f32 v168, v8, v9
	v_cvt_pk_bf16_f32 v169, v10, v11
	s_mov_b64 exec, -1
	global_store_dwordx4 v122, v[166:169], s[24:25] offset:2048
	s_nop 1
	s_mov_b64 exec, -1
	v_mov_b32_e32 v100, v2
	v_lshrrev_b32_e32 v102, 1, v100
	v_sub_u32_e32 v104, s0, v102
	v_max_i32_e32 v106, 0, v104
	v_sub_u32_e32 v108, 0, v104
	v_max_i32_e32 v108, 0, v108
	v_and_b32_e32 v118, 1, v100
	v_lshlrev_b32_e32 v118, 5, v118
	v_add_u32_e32 v118, s41, v118
	v_add_u32_e32 v118, 0x80, v118
	v_lshl_add_u32 v110, v106, 10, v118
	v_lshl_add_u32 v112, v108, 10, v118
	v_add_u32_e32 v112, 0x8000, v112
	v_add_u32_e32 v114, 0x1e400, v118
	ds_read_b128 v[12:15], v110
	ds_read_b128 v[16:19], v110 offset:16
	ds_read_b128 v[124:127], v112
	ds_read_b128 v[128:131], v112 offset:16
	ds_read_b128 v[132:135], v114
	ds_read_b128 v[136:139], v114 offset:16
	s_waitcnt lgkmcnt(0)
	v_cmp_le_i32_e32 vcc, 0, v104
	v_cndmask_b32_e32 v4, 0, v12, vcc
	v_cndmask_b32_e32 v5, 0, v13, vcc
	v_cndmask_b32_e32 v6, 0, v14, vcc
	v_cndmask_b32_e32 v7, 0, v15, vcc
	v_cndmask_b32_e32 v8, 0, v16, vcc
	v_cndmask_b32_e32 v9, 0, v17, vcc
	v_cndmask_b32_e32 v10, 0, v18, vcc
	v_cndmask_b32_e32 v11, 0, v19, vcc
	v_cmp_ge_i32_e32 vcc, 0, v104
	v_cndmask_b32_e32 v124, 0, v124, vcc
	v_cndmask_b32_e32 v125, 0, v125, vcc
	v_cndmask_b32_e32 v126, 0, v126, vcc
	v_cndmask_b32_e32 v127, 0, v127, vcc
	v_cndmask_b32_e32 v128, 0, v128, vcc
	v_cndmask_b32_e32 v129, 0, v129, vcc
	v_cndmask_b32_e32 v130, 0, v130, vcc
	v_cndmask_b32_e32 v131, 0, v131, vcc
	v_add_f32_e32 v4, v4, v124
	v_add_f32_e32 v5, v5, v125
	v_add_f32_e32 v6, v6, v126
	v_add_f32_e32 v7, v7, v127
	v_add_f32_e32 v8, v8, v128
	v_add_f32_e32 v9, v9, v129
	v_add_f32_e32 v10, v10, v130
	v_add_f32_e32 v11, v11, v131
	v_cmp_eq_u32_e32 vcc, 0, v104
	v_cndmask_b32_e32 v132, 0, v132, vcc
	v_cndmask_b32_e32 v133, 0, v133, vcc
	v_cndmask_b32_e32 v134, 0, v134, vcc
	v_cndmask_b32_e32 v135, 0, v135, vcc
	v_cndmask_b32_e32 v136, 0, v136, vcc
	v_cndmask_b32_e32 v137, 0, v137, vcc
	v_cndmask_b32_e32 v138, 0, v138, vcc
	v_cndmask_b32_e32 v139, 0, v139, vcc
	v_add_f32_e32 v4, v4, v132
	v_add_f32_e32 v5, v5, v133
	v_add_f32_e32 v6, v6, v134
	v_add_f32_e32 v7, v7, v135
	v_add_f32_e32 v8, v8, v136
	v_add_f32_e32 v9, v9, v137
	v_add_f32_e32 v10, v10, v138
	v_add_f32_e32 v11, v11, v139
	v_cvt_pk_bf16_f32 v166, v4, v5
	v_cvt_pk_bf16_f32 v167, v6, v7
	v_cvt_pk_bf16_f32 v168, v8, v9
	v_cvt_pk_bf16_f32 v169, v10, v11
	s_mov_b64 exec, -1
	global_store_dwordx4 v122, v[166:169], s[24:25] offset:3072
	s_add_u32 s24, s24, 0x1000
	s_addc_u32 s25, s25, 0
	s_nop 1
	s_mov_b32 exec_lo, -1
	s_mov_b32 exec_hi, 0
	v_mov_b32_e32 v100, v2
	v_lshrrev_b32_e32 v102, 4, v100
	v_and_b32_e32 v118, 7, v100
	v_lshlrev_b32_e32 v118, 3, v118
	v_cmp_ne_u32_e32 vcc, 0, v102
	v_cndmask_b32_e32 v106, v140, v142, vcc
	v_lshl_add_u32 v120, v102, 6, v118
	v_mul_u32_u24_e32 v120, 0x108, v120
	v_lshl_add_u32 v110, v106, 3, v120
	v_add_u32_e32 v110, 0x10000, v110
	v_lshlrev_b32_e32 v112, 2, v118
	v_add_u32_e32 v112, s41, v112
	ds_read_b64 v[20:21], v110
	ds_read_b64 v[98:99], v110 offset:264
	ds_read_b64 v[116:117], v110 offset:528
	ds_read_b64 v[148:149], v110 offset:792
	ds_read_b64 v[150:151], v110 offset:1056
	ds_read_b64 v[152:153], v110 offset:1320
	ds_read_b64 v[154:155], v110 offset:1584
	ds_read_b64 v[164:165], v110 offset:1848
	v_lshlrev_b32_e32 v112, 2, v118
	s_lshl_b32 s36, s41, 2
	v_add_u32_e32 v112, s36, v112
	v_add_u32_e32 v112, 0x1c600, v112
	ds_read_b128 v[12:15], v112
	ds_read_b128 v[16:19], v112 offset:16
	ds_read_b128 v[124:127], v112 offset:4096
	ds_read_b128 v[128:131], v112 offset:4112
	v_bfe_u32 v108, v100, 3, 1
	s_waitcnt lgkmcnt(0)
	v_cmp_ne_u32_e32 vcc, 0, v108
	v_mul_f32_e32 v170, v12, v20
	v_mul_f32_e32 v171, v124, v21
	v_mul_f32_e32 v172, v12, v21
	v_mul_f32_e32 v173, v124, v20
	v_sub_f32_e32 v170, v170, v171
	v_add_f32_e32 v172, v172, v173
	v_xor_b32_e32 v172, 0x80000000, v172
	v_cndmask_b32_e32 v4, v170, v172, vcc
	v_mul_f32_e32 v170, v13, v98
	v_mul_f32_e32 v171, v125, v99
	v_mul_f32_e32 v172, v13, v99
	v_mul_f32_e32 v173, v125, v98
	v_sub_f32_e32 v170, v170, v171
	v_add_f32_e32 v172, v172, v173
	v_xor_b32_e32 v172, 0x80000000, v172
	v_cndmask_b32_e32 v5, v170, v172, vcc
	v_mul_f32_e32 v170, v14, v116
	v_mul_f32_e32 v171, v126, v117
	v_mul_f32_e32 v172, v14, v117
	v_mul_f32_e32 v173, v126, v116
	v_sub_f32_e32 v170, v170, v171
	v_add_f32_e32 v172, v172, v173
	v_xor_b32_e32 v172, 0x80000000, v172
	v_cndmask_b32_e32 v6, v170, v172, vcc
	v_mul_f32_e32 v170, v15, v148
	v_mul_f32_e32 v171, v127, v149
	v_mul_f32_e32 v172, v15, v149
	v_mul_f32_e32 v173, v127, v148
	v_sub_f32_e32 v170, v170, v171
	v_add_f32_e32 v172, v172, v173
	v_xor_b32_e32 v172, 0x80000000, v172
	v_cndmask_b32_e32 v7, v170, v172, vcc
	v_mul_f32_e32 v170, v16, v150
	v_mul_f32_e32 v171, v128, v151
	v_mul_f32_e32 v172, v16, v151
	v_mul_f32_e32 v173, v128, v150
	v_sub_f32_e32 v170, v170, v171
	v_add_f32_e32 v172, v172, v173
	v_xor_b32_e32 v172, 0x80000000, v172
	v_cndmask_b32_e32 v8, v170, v172, vcc
	v_mul_f32_e32 v170, v17, v152
	v_mul_f32_e32 v171, v129, v153
	v_mul_f32_e32 v172, v17, v153
	v_mul_f32_e32 v173, v129, v152
	v_sub_f32_e32 v170, v170, v171
	v_add_f32_e32 v172, v172, v173
	v_xor_b32_e32 v172, 0x80000000, v172
	v_cndmask_b32_e32 v9, v170, v172, vcc
	v_mul_f32_e32 v170, v18, v154
	v_mul_f32_e32 v171, v130, v155
	v_mul_f32_e32 v172, v18, v155
	v_mul_f32_e32 v173, v130, v154
	v_sub_f32_e32 v170, v170, v171
	v_add_f32_e32 v172, v172, v173
	v_xor_b32_e32 v172, 0x80000000, v172
	v_cndmask_b32_e32 v10, v170, v172, vcc
	v_mul_f32_e32 v170, v19, v164
	v_mul_f32_e32 v171, v131, v165
	v_mul_f32_e32 v172, v19, v165
	v_mul_f32_e32 v173, v131, v164
	v_sub_f32_e32 v170, v170, v171
	v_add_f32_e32 v172, v172, v173
	v_xor_b32_e32 v172, 0x80000000, v172
	v_cndmask_b32_e32 v11, v170, v172, vcc
	v_cvt_pk_bf16_f32 v166, v4, v5
	v_cvt_pk_bf16_f32 v167, v6, v7
	v_cvt_pk_bf16_f32 v168, v8, v9
	v_cvt_pk_bf16_f32 v169, v10, v11
	s_mov_b32 exec_lo, 0
	s_mov_b32 exec_hi, -1
	v_add_u32_e32 v100, 0xffffffe0, v2
	v_lshrrev_b32_e32 v102, 1, v100
	v_sub_u32_e32 v104, s0, v102
	v_max_i32_e32 v106, 0, v104
	v_sub_u32_e32 v108, 0, v104
	v_max_i32_e32 v108, 0, v108
	v_and_b32_e32 v118, 1, v100
	v_lshlrev_b32_e32 v118, 5, v118
	v_add_u32_e32 v118, s41, v118
	v_add_u32_e32 v118, 0xc0, v118
	v_lshl_add_u32 v110, v106, 10, v118
	v_lshl_add_u32 v112, v108, 10, v118
	v_add_u32_e32 v112, 0x8000, v112
	v_add_u32_e32 v114, 0x1e400, v118
	ds_read_b128 v[12:15], v110
	ds_read_b128 v[16:19], v110 offset:16
	ds_read_b128 v[124:127], v112
	ds_read_b128 v[128:131], v112 offset:16
	ds_read_b128 v[132:135], v114
	ds_read_b128 v[136:139], v114 offset:16
	s_waitcnt lgkmcnt(0)
	v_cmp_le_i32_e32 vcc, 0, v104
	v_cndmask_b32_e32 v4, 0, v12, vcc
	v_cndmask_b32_e32 v5, 0, v13, vcc
	v_cndmask_b32_e32 v6, 0, v14, vcc
	v_cndmask_b32_e32 v7, 0, v15, vcc
	v_cndmask_b32_e32 v8, 0, v16, vcc
	v_cndmask_b32_e32 v9, 0, v17, vcc
	v_cndmask_b32_e32 v10, 0, v18, vcc
	v_cndmask_b32_e32 v11, 0, v19, vcc
	v_cmp_ge_i32_e32 vcc, 0, v104
	v_cndmask_b32_e32 v124, 0, v124, vcc
	v_cndmask_b32_e32 v125, 0, v125, vcc
	v_cndmask_b32_e32 v126, 0, v126, vcc
	v_cndmask_b32_e32 v127, 0, v127, vcc
	v_cndmask_b32_e32 v128, 0, v128, vcc
	v_cndmask_b32_e32 v129, 0, v129, vcc
	v_cndmask_b32_e32 v130, 0, v130, vcc
	v_cndmask_b32_e32 v131, 0, v131, vcc
	v_add_f32_e32 v4, v4, v124
	v_add_f32_e32 v5, v5, v125
	v_add_f32_e32 v6, v6, v126
	v_add_f32_e32 v7, v7, v127
	v_add_f32_e32 v8, v8, v128
	v_add_f32_e32 v9, v9, v129
	v_add_f32_e32 v10, v10, v130
	v_add_f32_e32 v11, v11, v131
	v_cmp_eq_u32_e32 vcc, 0, v104
	v_cndmask_b32_e32 v132, 0, v132, vcc
	v_cndmask_b32_e32 v133, 0, v133, vcc
	v_cndmask_b32_e32 v134, 0, v134, vcc
	v_cndmask_b32_e32 v135, 0, v135, vcc
	v_cndmask_b32_e32 v136, 0, v136, vcc
	v_cndmask_b32_e32 v137, 0, v137, vcc
	v_cndmask_b32_e32 v138, 0, v138, vcc
	v_cndmask_b32_e32 v139, 0, v139, vcc
	v_add_f32_e32 v4, v4, v132
	v_add_f32_e32 v5, v5, v133
	v_add_f32_e32 v6, v6, v134
	v_add_f32_e32 v7, v7, v135
	v_add_f32_e32 v8, v8, v136
	v_add_f32_e32 v9, v9, v137
	v_add_f32_e32 v10, v10, v138
	v_add_f32_e32 v11, v11, v139
	v_cvt_pk_bf16_f32 v166, v4, v5
	v_cvt_pk_bf16_f32 v167, v6, v7
	v_cvt_pk_bf16_f32 v168, v8, v9
	v_cvt_pk_bf16_f32 v169, v10, v11
	s_mov_b64 exec, -1
	global_store_dwordx4 v122, v[166:169], s[24:25]
	s_nop 1
	s_mov_b32 exec_lo, -1
	s_mov_b32 exec_hi, 0
	v_add_u32_e32 v100, 32, v2
	v_lshrrev_b32_e32 v102, 1, v100
	v_sub_u32_e32 v104, s0, v102
	v_max_i32_e32 v106, 0, v104
	v_sub_u32_e32 v108, 0, v104
	v_max_i32_e32 v108, 0, v108
	v_and_b32_e32 v118, 1, v100
	v_lshlrev_b32_e32 v118, 5, v118
	v_add_u32_e32 v118, s41, v118
	v_add_u32_e32 v118, 0xc0, v118
	v_lshl_add_u32 v110, v106, 10, v118
	v_lshl_add_u32 v112, v108, 10, v118
	v_add_u32_e32 v112, 0x8000, v112
	v_add_u32_e32 v114, 0x1e400, v118
	ds_read_b128 v[12:15], v110
	ds_read_b128 v[16:19], v110 offset:16
	ds_read_b128 v[124:127], v112
	ds_read_b128 v[128:131], v112 offset:16
	ds_read_b128 v[132:135], v114
	ds_read_b128 v[136:139], v114 offset:16
	s_waitcnt lgkmcnt(0)
	v_cmp_le_i32_e32 vcc, 0, v104
	v_cndmask_b32_e32 v4, 0, v12, vcc
	v_cndmask_b32_e32 v5, 0, v13, vcc
	v_cndmask_b32_e32 v6, 0, v14, vcc
	v_cndmask_b32_e32 v7, 0, v15, vcc
	v_cndmask_b32_e32 v8, 0, v16, vcc
	v_cndmask_b32_e32 v9, 0, v17, vcc
	v_cndmask_b32_e32 v10, 0, v18, vcc
	v_cndmask_b32_e32 v11, 0, v19, vcc
	v_cmp_ge_i32_e32 vcc, 0, v104
	v_cndmask_b32_e32 v124, 0, v124, vcc
	v_cndmask_b32_e32 v125, 0, v125, vcc
	v_cndmask_b32_e32 v126, 0, v126, vcc
	v_cndmask_b32_e32 v127, 0, v127, vcc
	v_cndmask_b32_e32 v128, 0, v128, vcc
	v_cndmask_b32_e32 v129, 0, v129, vcc
	v_cndmask_b32_e32 v130, 0, v130, vcc
	v_cndmask_b32_e32 v131, 0, v131, vcc
	v_add_f32_e32 v4, v4, v124
	v_add_f32_e32 v5, v5, v125
	v_add_f32_e32 v6, v6, v126
	v_add_f32_e32 v7, v7, v127
	v_add_f32_e32 v8, v8, v128
	v_add_f32_e32 v9, v9, v129
	v_add_f32_e32 v10, v10, v130
	v_add_f32_e32 v11, v11, v131
	v_cmp_eq_u32_e32 vcc, 0, v104
	v_cndmask_b32_e32 v132, 0, v132, vcc
	v_cndmask_b32_e32 v133, 0, v133, vcc
	v_cndmask_b32_e32 v134, 0, v134, vcc
	v_cndmask_b32_e32 v135, 0, v135, vcc
	v_cndmask_b32_e32 v136, 0, v136, vcc
	v_cndmask_b32_e32 v137, 0, v137, vcc
	v_cndmask_b32_e32 v138, 0, v138, vcc
	v_cndmask_b32_e32 v139, 0, v139, vcc
	v_add_f32_e32 v4, v4, v132
	v_add_f32_e32 v5, v5, v133
	v_add_f32_e32 v6, v6, v134
	v_add_f32_e32 v7, v7, v135
	v_add_f32_e32 v8, v8, v136
	v_add_f32_e32 v9, v9, v137
	v_add_f32_e32 v10, v10, v138
	v_add_f32_e32 v11, v11, v139
	v_cvt_pk_bf16_f32 v166, v4, v5
	v_cvt_pk_bf16_f32 v167, v6, v7
	v_cvt_pk_bf16_f32 v168, v8, v9
	v_cvt_pk_bf16_f32 v169, v10, v11
	s_mov_b32 exec_lo, 0
	s_mov_b32 exec_hi, -1
	v_subrev_u32_e32 v100, 32, v2
	v_lshrrev_b32_e32 v102, 4, v100
	v_and_b32_e32 v118, 7, v100
	v_lshlrev_b32_e32 v118, 3, v118
	v_cmp_ne_u32_e32 vcc, 0, v102
	v_cndmask_b32_e32 v106, v140, v142, vcc
	v_lshl_add_u32 v120, v102, 6, v118
	v_mul_u32_u24_e32 v120, 0x108, v120
	v_lshl_add_u32 v110, v106, 3, v120
	v_add_u32_e32 v110, 0x10000, v110
	v_lshlrev_b32_e32 v112, 2, v118
	v_add_u32_e32 v112, s41, v112
	ds_read_b64 v[20:21], v110
	ds_read_b64 v[98:99], v110 offset:264
	ds_read_b64 v[116:117], v110 offset:528
	ds_read_b64 v[148:149], v110 offset:792
	ds_read_b64 v[150:151], v110 offset:1056
	ds_read_b64 v[152:153], v110 offset:1320
	ds_read_b64 v[154:155], v110 offset:1584
	ds_read_b64 v[164:165], v110 offset:1848
	v_lshlrev_b32_e32 v112, 2, v118
	s_lshl_b32 s36, s41, 2
	v_add_u32_e32 v112, s36, v112
	v_add_u32_e32 v112, 0x1c700, v112
	ds_read_b128 v[12:15], v112
	ds_read_b128 v[16:19], v112 offset:16
	ds_read_b128 v[124:127], v112 offset:4096
	ds_read_b128 v[128:131], v112 offset:4112
	v_bfe_u32 v108, v100, 3, 1
	s_waitcnt lgkmcnt(0)
	v_cmp_ne_u32_e32 vcc, 0, v108
	v_mul_f32_e32 v170, v12, v20
	v_mul_f32_e32 v171, v124, v21
	v_mul_f32_e32 v172, v12, v21
	v_mul_f32_e32 v173, v124, v20
	v_sub_f32_e32 v170, v170, v171
	v_add_f32_e32 v172, v172, v173
	v_xor_b32_e32 v172, 0x80000000, v172
	v_cndmask_b32_e32 v4, v170, v172, vcc
	v_mul_f32_e32 v170, v13, v98
	v_mul_f32_e32 v171, v125, v99
	v_mul_f32_e32 v172, v13, v99
	v_mul_f32_e32 v173, v125, v98
	v_sub_f32_e32 v170, v170, v171
	v_add_f32_e32 v172, v172, v173
	v_xor_b32_e32 v172, 0x80000000, v172
	v_cndmask_b32_e32 v5, v170, v172, vcc
	v_mul_f32_e32 v170, v14, v116
	v_mul_f32_e32 v171, v126, v117
	v_mul_f32_e32 v172, v14, v117
	v_mul_f32_e32 v173, v126, v116
	v_sub_f32_e32 v170, v170, v171
	v_add_f32_e32 v172, v172, v173
	v_xor_b32_e32 v172, 0x80000000, v172
	v_cndmask_b32_e32 v6, v170, v172, vcc
	v_mul_f32_e32 v170, v15, v148
	v_mul_f32_e32 v171, v127, v149
	v_mul_f32_e32 v172, v15, v149
	v_mul_f32_e32 v173, v127, v148
	v_sub_f32_e32 v170, v170, v171
	v_add_f32_e32 v172, v172, v173
	v_xor_b32_e32 v172, 0x80000000, v172
	v_cndmask_b32_e32 v7, v170, v172, vcc
	v_mul_f32_e32 v170, v16, v150
	v_mul_f32_e32 v171, v128, v151
	v_mul_f32_e32 v172, v16, v151
	v_mul_f32_e32 v173, v128, v150
	v_sub_f32_e32 v170, v170, v171
	v_add_f32_e32 v172, v172, v173
	v_xor_b32_e32 v172, 0x80000000, v172
	v_cndmask_b32_e32 v8, v170, v172, vcc
	v_mul_f32_e32 v170, v17, v152
	v_mul_f32_e32 v171, v129, v153
	v_mul_f32_e32 v172, v17, v153
	v_mul_f32_e32 v173, v129, v152
	v_sub_f32_e32 v170, v170, v171
	v_add_f32_e32 v172, v172, v173
	v_xor_b32_e32 v172, 0x80000000, v172
	v_cndmask_b32_e32 v9, v170, v172, vcc
	v_mul_f32_e32 v170, v18, v154
	v_mul_f32_e32 v171, v130, v155
	v_mul_f32_e32 v172, v18, v155
	v_mul_f32_e32 v173, v130, v154
	v_sub_f32_e32 v170, v170, v171
	v_add_f32_e32 v172, v172, v173
	v_xor_b32_e32 v172, 0x80000000, v172
	v_cndmask_b32_e32 v10, v170, v172, vcc
	v_mul_f32_e32 v170, v19, v164
	v_mul_f32_e32 v171, v131, v165
	v_mul_f32_e32 v172, v19, v165
	v_mul_f32_e32 v173, v131, v164
	v_sub_f32_e32 v170, v170, v171
	v_add_f32_e32 v172, v172, v173
	v_xor_b32_e32 v172, 0x80000000, v172
	v_cndmask_b32_e32 v11, v170, v172, vcc
	v_cvt_pk_bf16_f32 v166, v4, v5
	v_cvt_pk_bf16_f32 v167, v6, v7
	v_cvt_pk_bf16_f32 v168, v8, v9
	v_cvt_pk_bf16_f32 v169, v10, v11
	s_mov_b64 exec, -1
	global_store_dwordx4 v122, v[166:169], s[24:25] offset:1024
	s_nop 1
	s_mov_b64 exec, -1
	v_mov_b32_e32 v100, v2
	v_lshrrev_b32_e32 v102, 1, v100
	v_sub_u32_e32 v104, s0, v102
	v_max_i32_e32 v106, 0, v104
	v_sub_u32_e32 v108, 0, v104
	v_max_i32_e32 v108, 0, v108
	v_and_b32_e32 v118, 1, v100
	v_lshlrev_b32_e32 v118, 5, v118
	v_add_u32_e32 v118, s41, v118
	v_add_u32_e32 v118, 0x100, v118
	v_lshl_add_u32 v110, v106, 10, v118
	v_lshl_add_u32 v112, v108, 10, v118
	v_add_u32_e32 v112, 0x8000, v112
	v_add_u32_e32 v114, 0x1e400, v118
	ds_read_b128 v[12:15], v110
	ds_read_b128 v[16:19], v110 offset:16
	ds_read_b128 v[124:127], v112
	ds_read_b128 v[128:131], v112 offset:16
	ds_read_b128 v[132:135], v114
	ds_read_b128 v[136:139], v114 offset:16
	s_waitcnt lgkmcnt(0)
	v_cmp_le_i32_e32 vcc, 0, v104
	v_cndmask_b32_e32 v4, 0, v12, vcc
	v_cndmask_b32_e32 v5, 0, v13, vcc
	v_cndmask_b32_e32 v6, 0, v14, vcc
	v_cndmask_b32_e32 v7, 0, v15, vcc
	v_cndmask_b32_e32 v8, 0, v16, vcc
	v_cndmask_b32_e32 v9, 0, v17, vcc
	v_cndmask_b32_e32 v10, 0, v18, vcc
	v_cndmask_b32_e32 v11, 0, v19, vcc
	v_cmp_ge_i32_e32 vcc, 0, v104
	v_cndmask_b32_e32 v124, 0, v124, vcc
	v_cndmask_b32_e32 v125, 0, v125, vcc
	v_cndmask_b32_e32 v126, 0, v126, vcc
	v_cndmask_b32_e32 v127, 0, v127, vcc
	v_cndmask_b32_e32 v128, 0, v128, vcc
	v_cndmask_b32_e32 v129, 0, v129, vcc
	v_cndmask_b32_e32 v130, 0, v130, vcc
	v_cndmask_b32_e32 v131, 0, v131, vcc
	v_add_f32_e32 v4, v4, v124
	v_add_f32_e32 v5, v5, v125
	v_add_f32_e32 v6, v6, v126
	v_add_f32_e32 v7, v7, v127
	v_add_f32_e32 v8, v8, v128
	v_add_f32_e32 v9, v9, v129
	v_add_f32_e32 v10, v10, v130
	v_add_f32_e32 v11, v11, v131
	v_cmp_eq_u32_e32 vcc, 0, v104
	v_cndmask_b32_e32 v132, 0, v132, vcc
	v_cndmask_b32_e32 v133, 0, v133, vcc
	v_cndmask_b32_e32 v134, 0, v134, vcc
	v_cndmask_b32_e32 v135, 0, v135, vcc
	v_cndmask_b32_e32 v136, 0, v136, vcc
	v_cndmask_b32_e32 v137, 0, v137, vcc
	v_cndmask_b32_e32 v138, 0, v138, vcc
	v_cndmask_b32_e32 v139, 0, v139, vcc
	v_add_f32_e32 v4, v4, v132
	v_add_f32_e32 v5, v5, v133
	v_add_f32_e32 v6, v6, v134
	v_add_f32_e32 v7, v7, v135
	v_add_f32_e32 v8, v8, v136
	v_add_f32_e32 v9, v9, v137
	v_add_f32_e32 v10, v10, v138
	v_add_f32_e32 v11, v11, v139
	v_cvt_pk_bf16_f32 v166, v4, v5
	v_cvt_pk_bf16_f32 v167, v6, v7
	v_cvt_pk_bf16_f32 v168, v8, v9
	v_cvt_pk_bf16_f32 v169, v10, v11
	s_mov_b64 exec, -1
	global_store_dwordx4 v122, v[166:169], s[24:25] offset:2048
	s_nop 1
	s_mov_b32 exec_lo, -1
	s_mov_b32 exec_hi, 0
	v_mov_b32_e32 v100, v2
	v_lshrrev_b32_e32 v102, 4, v100
	v_and_b32_e32 v118, 7, v100
	v_lshlrev_b32_e32 v118, 3, v118
	v_cmp_ne_u32_e32 vcc, 0, v102
	v_cndmask_b32_e32 v106, v140, v142, vcc
	v_lshl_add_u32 v120, v102, 6, v118
	v_mul_u32_u24_e32 v120, 0x108, v120
	v_lshl_add_u32 v110, v106, 3, v120
	v_add_u32_e32 v110, 0x10000, v110
	v_lshlrev_b32_e32 v112, 2, v118
	v_add_u32_e32 v112, s41, v112
	ds_read_b64 v[20:21], v110
	ds_read_b64 v[98:99], v110 offset:264
	ds_read_b64 v[116:117], v110 offset:528
	ds_read_b64 v[148:149], v110 offset:792
	ds_read_b64 v[150:151], v110 offset:1056
	ds_read_b64 v[152:153], v110 offset:1320
	ds_read_b64 v[154:155], v110 offset:1584
	ds_read_b64 v[164:165], v110 offset:1848
	v_lshlrev_b32_e32 v112, 2, v118
	s_lshl_b32 s36, s41, 2
	v_add_u32_e32 v112, s36, v112
	v_add_u32_e32 v112, 0x1c800, v112
	ds_read_b128 v[12:15], v112
	ds_read_b128 v[16:19], v112 offset:16
	ds_read_b128 v[124:127], v112 offset:4096
	ds_read_b128 v[128:131], v112 offset:4112
	v_bfe_u32 v108, v100, 3, 1
	s_waitcnt lgkmcnt(0)
	v_cmp_ne_u32_e32 vcc, 0, v108
	v_mul_f32_e32 v170, v12, v20
	v_mul_f32_e32 v171, v124, v21
	v_mul_f32_e32 v172, v12, v21
	v_mul_f32_e32 v173, v124, v20
	v_sub_f32_e32 v170, v170, v171
	v_add_f32_e32 v172, v172, v173
	v_xor_b32_e32 v172, 0x80000000, v172
	v_cndmask_b32_e32 v4, v170, v172, vcc
	v_mul_f32_e32 v170, v13, v98
	v_mul_f32_e32 v171, v125, v99
	v_mul_f32_e32 v172, v13, v99
	v_mul_f32_e32 v173, v125, v98
	v_sub_f32_e32 v170, v170, v171
	v_add_f32_e32 v172, v172, v173
	v_xor_b32_e32 v172, 0x80000000, v172
	v_cndmask_b32_e32 v5, v170, v172, vcc
	v_mul_f32_e32 v170, v14, v116
	v_mul_f32_e32 v171, v126, v117
	v_mul_f32_e32 v172, v14, v117
	v_mul_f32_e32 v173, v126, v116
	v_sub_f32_e32 v170, v170, v171
	v_add_f32_e32 v172, v172, v173
	v_xor_b32_e32 v172, 0x80000000, v172
	v_cndmask_b32_e32 v6, v170, v172, vcc
	v_mul_f32_e32 v170, v15, v148
	v_mul_f32_e32 v171, v127, v149
	v_mul_f32_e32 v172, v15, v149
	v_mul_f32_e32 v173, v127, v148
	v_sub_f32_e32 v170, v170, v171
	v_add_f32_e32 v172, v172, v173
	v_xor_b32_e32 v172, 0x80000000, v172
	v_cndmask_b32_e32 v7, v170, v172, vcc
	v_mul_f32_e32 v170, v16, v150
	v_mul_f32_e32 v171, v128, v151
	v_mul_f32_e32 v172, v16, v151
	v_mul_f32_e32 v173, v128, v150
	v_sub_f32_e32 v170, v170, v171
	v_add_f32_e32 v172, v172, v173
	v_xor_b32_e32 v172, 0x80000000, v172
	v_cndmask_b32_e32 v8, v170, v172, vcc
	v_mul_f32_e32 v170, v17, v152
	v_mul_f32_e32 v171, v129, v153
	v_mul_f32_e32 v172, v17, v153
	v_mul_f32_e32 v173, v129, v152
	v_sub_f32_e32 v170, v170, v171
	v_add_f32_e32 v172, v172, v173
	v_xor_b32_e32 v172, 0x80000000, v172
	v_cndmask_b32_e32 v9, v170, v172, vcc
	v_mul_f32_e32 v170, v18, v154
	v_mul_f32_e32 v171, v130, v155
	v_mul_f32_e32 v172, v18, v155
	v_mul_f32_e32 v173, v130, v154
	v_sub_f32_e32 v170, v170, v171
	v_add_f32_e32 v172, v172, v173
	v_xor_b32_e32 v172, 0x80000000, v172
	v_cndmask_b32_e32 v10, v170, v172, vcc
	v_mul_f32_e32 v170, v19, v164
	v_mul_f32_e32 v171, v131, v165
	v_mul_f32_e32 v172, v19, v165
	v_mul_f32_e32 v173, v131, v164
	v_sub_f32_e32 v170, v170, v171
	v_add_f32_e32 v172, v172, v173
	v_xor_b32_e32 v172, 0x80000000, v172
	v_cndmask_b32_e32 v11, v170, v172, vcc
	v_cvt_pk_bf16_f32 v166, v4, v5
	v_cvt_pk_bf16_f32 v167, v6, v7
	v_cvt_pk_bf16_f32 v168, v8, v9
	v_cvt_pk_bf16_f32 v169, v10, v11
	s_mov_b32 exec_lo, 0
	s_mov_b32 exec_hi, -1
	v_add_u32_e32 v100, 0xffffffe0, v2
	v_lshrrev_b32_e32 v102, 1, v100
	v_sub_u32_e32 v104, s0, v102
	v_max_i32_e32 v106, 0, v104
	v_sub_u32_e32 v108, 0, v104
	v_max_i32_e32 v108, 0, v108
	v_and_b32_e32 v118, 1, v100
	v_lshlrev_b32_e32 v118, 5, v118
	v_add_u32_e32 v118, s41, v118
	v_add_u32_e32 v118, 0x140, v118
	v_lshl_add_u32 v110, v106, 10, v118
	v_lshl_add_u32 v112, v108, 10, v118
	v_add_u32_e32 v112, 0x8000, v112
	v_add_u32_e32 v114, 0x1e400, v118
	ds_read_b128 v[12:15], v110
	ds_read_b128 v[16:19], v110 offset:16
	ds_read_b128 v[124:127], v112
	ds_read_b128 v[128:131], v112 offset:16
	ds_read_b128 v[132:135], v114
	ds_read_b128 v[136:139], v114 offset:16
	s_waitcnt lgkmcnt(0)
	v_cmp_le_i32_e32 vcc, 0, v104
	v_cndmask_b32_e32 v4, 0, v12, vcc
	v_cndmask_b32_e32 v5, 0, v13, vcc
	v_cndmask_b32_e32 v6, 0, v14, vcc
	v_cndmask_b32_e32 v7, 0, v15, vcc
	v_cndmask_b32_e32 v8, 0, v16, vcc
	v_cndmask_b32_e32 v9, 0, v17, vcc
	v_cndmask_b32_e32 v10, 0, v18, vcc
	v_cndmask_b32_e32 v11, 0, v19, vcc
	v_cmp_ge_i32_e32 vcc, 0, v104
	v_cndmask_b32_e32 v124, 0, v124, vcc
	v_cndmask_b32_e32 v125, 0, v125, vcc
	v_cndmask_b32_e32 v126, 0, v126, vcc
	v_cndmask_b32_e32 v127, 0, v127, vcc
	v_cndmask_b32_e32 v128, 0, v128, vcc
	v_cndmask_b32_e32 v129, 0, v129, vcc
	v_cndmask_b32_e32 v130, 0, v130, vcc
	v_cndmask_b32_e32 v131, 0, v131, vcc
	v_add_f32_e32 v4, v4, v124
	v_add_f32_e32 v5, v5, v125
	v_add_f32_e32 v6, v6, v126
	v_add_f32_e32 v7, v7, v127
	v_add_f32_e32 v8, v8, v128
	v_add_f32_e32 v9, v9, v129
	v_add_f32_e32 v10, v10, v130
	v_add_f32_e32 v11, v11, v131
	v_cmp_eq_u32_e32 vcc, 0, v104
	v_cndmask_b32_e32 v132, 0, v132, vcc
	v_cndmask_b32_e32 v133, 0, v133, vcc
	v_cndmask_b32_e32 v134, 0, v134, vcc
	v_cndmask_b32_e32 v135, 0, v135, vcc
	v_cndmask_b32_e32 v136, 0, v136, vcc
	v_cndmask_b32_e32 v137, 0, v137, vcc
	v_cndmask_b32_e32 v138, 0, v138, vcc
	v_cndmask_b32_e32 v139, 0, v139, vcc
	v_add_f32_e32 v4, v4, v132
	v_add_f32_e32 v5, v5, v133
	v_add_f32_e32 v6, v6, v134
	v_add_f32_e32 v7, v7, v135
	v_add_f32_e32 v8, v8, v136
	v_add_f32_e32 v9, v9, v137
	v_add_f32_e32 v10, v10, v138
	v_add_f32_e32 v11, v11, v139
	v_cvt_pk_bf16_f32 v166, v4, v5
	v_cvt_pk_bf16_f32 v167, v6, v7
	v_cvt_pk_bf16_f32 v168, v8, v9
	v_cvt_pk_bf16_f32 v169, v10, v11
	s_mov_b64 exec, -1
	global_store_dwordx4 v122, v[166:169], s[24:25] offset:3072
	s_add_u32 s24, s24, 0x1000
	s_addc_u32 s25, s25, 0
	s_nop 1
	s_mov_b32 exec_lo, -1
	s_mov_b32 exec_hi, 0
	v_add_u32_e32 v100, 32, v2
	v_lshrrev_b32_e32 v102, 1, v100
	v_sub_u32_e32 v104, s0, v102
	v_max_i32_e32 v106, 0, v104
	v_sub_u32_e32 v108, 0, v104
	v_max_i32_e32 v108, 0, v108
	v_and_b32_e32 v118, 1, v100
	v_lshlrev_b32_e32 v118, 5, v118
	v_add_u32_e32 v118, s41, v118
	v_add_u32_e32 v118, 0x140, v118
	v_lshl_add_u32 v110, v106, 10, v118
	v_lshl_add_u32 v112, v108, 10, v118
	v_add_u32_e32 v112, 0x8000, v112
	v_add_u32_e32 v114, 0x1e400, v118
	ds_read_b128 v[12:15], v110
	ds_read_b128 v[16:19], v110 offset:16
	ds_read_b128 v[124:127], v112
	ds_read_b128 v[128:131], v112 offset:16
	ds_read_b128 v[132:135], v114
	ds_read_b128 v[136:139], v114 offset:16
	s_waitcnt lgkmcnt(0)
	v_cmp_le_i32_e32 vcc, 0, v104
	v_cndmask_b32_e32 v4, 0, v12, vcc
	v_cndmask_b32_e32 v5, 0, v13, vcc
	v_cndmask_b32_e32 v6, 0, v14, vcc
	v_cndmask_b32_e32 v7, 0, v15, vcc
	v_cndmask_b32_e32 v8, 0, v16, vcc
	v_cndmask_b32_e32 v9, 0, v17, vcc
	v_cndmask_b32_e32 v10, 0, v18, vcc
	v_cndmask_b32_e32 v11, 0, v19, vcc
	v_cmp_ge_i32_e32 vcc, 0, v104
	v_cndmask_b32_e32 v124, 0, v124, vcc
	v_cndmask_b32_e32 v125, 0, v125, vcc
	v_cndmask_b32_e32 v126, 0, v126, vcc
	v_cndmask_b32_e32 v127, 0, v127, vcc
	v_cndmask_b32_e32 v128, 0, v128, vcc
	v_cndmask_b32_e32 v129, 0, v129, vcc
	v_cndmask_b32_e32 v130, 0, v130, vcc
	v_cndmask_b32_e32 v131, 0, v131, vcc
	v_add_f32_e32 v4, v4, v124
	v_add_f32_e32 v5, v5, v125
	v_add_f32_e32 v6, v6, v126
	v_add_f32_e32 v7, v7, v127
	v_add_f32_e32 v8, v8, v128
	v_add_f32_e32 v9, v9, v129
	v_add_f32_e32 v10, v10, v130
	v_add_f32_e32 v11, v11, v131
	v_cmp_eq_u32_e32 vcc, 0, v104
	v_cndmask_b32_e32 v132, 0, v132, vcc
	v_cndmask_b32_e32 v133, 0, v133, vcc
	v_cndmask_b32_e32 v134, 0, v134, vcc
	v_cndmask_b32_e32 v135, 0, v135, vcc
	v_cndmask_b32_e32 v136, 0, v136, vcc
	v_cndmask_b32_e32 v137, 0, v137, vcc
	v_cndmask_b32_e32 v138, 0, v138, vcc
	v_cndmask_b32_e32 v139, 0, v139, vcc
	v_add_f32_e32 v4, v4, v132
	v_add_f32_e32 v5, v5, v133
	v_add_f32_e32 v6, v6, v134
	v_add_f32_e32 v7, v7, v135
	v_add_f32_e32 v8, v8, v136
	v_add_f32_e32 v9, v9, v137
	v_add_f32_e32 v10, v10, v138
	v_add_f32_e32 v11, v11, v139
	v_cvt_pk_bf16_f32 v166, v4, v5
	v_cvt_pk_bf16_f32 v167, v6, v7
	v_cvt_pk_bf16_f32 v168, v8, v9
	v_cvt_pk_bf16_f32 v169, v10, v11
	s_mov_b32 exec_lo, 0
	s_mov_b32 exec_hi, -1
	v_subrev_u32_e32 v100, 32, v2
	v_lshrrev_b32_e32 v102, 4, v100
	v_and_b32_e32 v118, 7, v100
	v_lshlrev_b32_e32 v118, 3, v118
	v_cmp_ne_u32_e32 vcc, 0, v102
	v_cndmask_b32_e32 v106, v140, v142, vcc
	v_lshl_add_u32 v120, v102, 6, v118
	v_mul_u32_u24_e32 v120, 0x108, v120
	v_lshl_add_u32 v110, v106, 3, v120
	v_add_u32_e32 v110, 0x10000, v110
	v_lshlrev_b32_e32 v112, 2, v118
	v_add_u32_e32 v112, s41, v112
	ds_read_b64 v[20:21], v110
	ds_read_b64 v[98:99], v110 offset:264
	ds_read_b64 v[116:117], v110 offset:528
	ds_read_b64 v[148:149], v110 offset:792
	ds_read_b64 v[150:151], v110 offset:1056
	ds_read_b64 v[152:153], v110 offset:1320
	ds_read_b64 v[154:155], v110 offset:1584
	ds_read_b64 v[164:165], v110 offset:1848
	v_lshlrev_b32_e32 v112, 2, v118
	s_lshl_b32 s36, s41, 2
	v_add_u32_e32 v112, s36, v112
	v_add_u32_e32 v112, 0x1c900, v112
	ds_read_b128 v[12:15], v112
	ds_read_b128 v[16:19], v112 offset:16
	ds_read_b128 v[124:127], v112 offset:4096
	ds_read_b128 v[128:131], v112 offset:4112
	v_bfe_u32 v108, v100, 3, 1
	s_waitcnt lgkmcnt(0)
	v_cmp_ne_u32_e32 vcc, 0, v108
	v_mul_f32_e32 v170, v12, v20
	v_mul_f32_e32 v171, v124, v21
	v_mul_f32_e32 v172, v12, v21
	v_mul_f32_e32 v173, v124, v20
	v_sub_f32_e32 v170, v170, v171
	v_add_f32_e32 v172, v172, v173
	v_xor_b32_e32 v172, 0x80000000, v172
	v_cndmask_b32_e32 v4, v170, v172, vcc
	v_mul_f32_e32 v170, v13, v98
	v_mul_f32_e32 v171, v125, v99
	v_mul_f32_e32 v172, v13, v99
	v_mul_f32_e32 v173, v125, v98
	v_sub_f32_e32 v170, v170, v171
	v_add_f32_e32 v172, v172, v173
	v_xor_b32_e32 v172, 0x80000000, v172
	v_cndmask_b32_e32 v5, v170, v172, vcc
	v_mul_f32_e32 v170, v14, v116
	v_mul_f32_e32 v171, v126, v117
	v_mul_f32_e32 v172, v14, v117
	v_mul_f32_e32 v173, v126, v116
	v_sub_f32_e32 v170, v170, v171
	v_add_f32_e32 v172, v172, v173
	v_xor_b32_e32 v172, 0x80000000, v172
	v_cndmask_b32_e32 v6, v170, v172, vcc
	v_mul_f32_e32 v170, v15, v148
	v_mul_f32_e32 v171, v127, v149
	v_mul_f32_e32 v172, v15, v149
	v_mul_f32_e32 v173, v127, v148
	v_sub_f32_e32 v170, v170, v171
	v_add_f32_e32 v172, v172, v173
	v_xor_b32_e32 v172, 0x80000000, v172
	v_cndmask_b32_e32 v7, v170, v172, vcc
	v_mul_f32_e32 v170, v16, v150
	v_mul_f32_e32 v171, v128, v151
	v_mul_f32_e32 v172, v16, v151
	v_mul_f32_e32 v173, v128, v150
	v_sub_f32_e32 v170, v170, v171
	v_add_f32_e32 v172, v172, v173
	v_xor_b32_e32 v172, 0x80000000, v172
	v_cndmask_b32_e32 v8, v170, v172, vcc
	v_mul_f32_e32 v170, v17, v152
	v_mul_f32_e32 v171, v129, v153
	v_mul_f32_e32 v172, v17, v153
	v_mul_f32_e32 v173, v129, v152
	v_sub_f32_e32 v170, v170, v171
	v_add_f32_e32 v172, v172, v173
	v_xor_b32_e32 v172, 0x80000000, v172
	v_cndmask_b32_e32 v9, v170, v172, vcc
	v_mul_f32_e32 v170, v18, v154
	v_mul_f32_e32 v171, v130, v155
	v_mul_f32_e32 v172, v18, v155
	v_mul_f32_e32 v173, v130, v154
	v_sub_f32_e32 v170, v170, v171
	v_add_f32_e32 v172, v172, v173
	v_xor_b32_e32 v172, 0x80000000, v172
	v_cndmask_b32_e32 v10, v170, v172, vcc
	v_mul_f32_e32 v170, v19, v164
	v_mul_f32_e32 v171, v131, v165
	v_mul_f32_e32 v172, v19, v165
	v_mul_f32_e32 v173, v131, v164
	v_sub_f32_e32 v170, v170, v171
	v_add_f32_e32 v172, v172, v173
	v_xor_b32_e32 v172, 0x80000000, v172
	v_cndmask_b32_e32 v11, v170, v172, vcc
	v_cvt_pk_bf16_f32 v166, v4, v5
	v_cvt_pk_bf16_f32 v167, v6, v7
	v_cvt_pk_bf16_f32 v168, v8, v9
	v_cvt_pk_bf16_f32 v169, v10, v11
	s_mov_b64 exec, -1
	global_store_dwordx4 v122, v[166:169], s[24:25]
	s_nop 1
	s_mov_b64 exec, -1
	v_mov_b32_e32 v100, v2
	v_lshrrev_b32_e32 v102, 1, v100
	v_sub_u32_e32 v104, s0, v102
	v_max_i32_e32 v106, 0, v104
	v_sub_u32_e32 v108, 0, v104
	v_max_i32_e32 v108, 0, v108
	v_and_b32_e32 v118, 1, v100
	v_lshlrev_b32_e32 v118, 5, v118
	v_add_u32_e32 v118, s41, v118
	v_add_u32_e32 v118, 0x180, v118
	v_lshl_add_u32 v110, v106, 10, v118
	v_lshl_add_u32 v112, v108, 10, v118
	v_add_u32_e32 v112, 0x8000, v112
	v_add_u32_e32 v114, 0x1e400, v118
	ds_read_b128 v[12:15], v110
	ds_read_b128 v[16:19], v110 offset:16
	ds_read_b128 v[124:127], v112
	ds_read_b128 v[128:131], v112 offset:16
	ds_read_b128 v[132:135], v114
	ds_read_b128 v[136:139], v114 offset:16
	s_waitcnt lgkmcnt(0)
	v_cmp_le_i32_e32 vcc, 0, v104
	v_cndmask_b32_e32 v4, 0, v12, vcc
	v_cndmask_b32_e32 v5, 0, v13, vcc
	v_cndmask_b32_e32 v6, 0, v14, vcc
	v_cndmask_b32_e32 v7, 0, v15, vcc
	v_cndmask_b32_e32 v8, 0, v16, vcc
	v_cndmask_b32_e32 v9, 0, v17, vcc
	v_cndmask_b32_e32 v10, 0, v18, vcc
	v_cndmask_b32_e32 v11, 0, v19, vcc
	v_cmp_ge_i32_e32 vcc, 0, v104
	v_cndmask_b32_e32 v124, 0, v124, vcc
	v_cndmask_b32_e32 v125, 0, v125, vcc
	v_cndmask_b32_e32 v126, 0, v126, vcc
	v_cndmask_b32_e32 v127, 0, v127, vcc
	v_cndmask_b32_e32 v128, 0, v128, vcc
	v_cndmask_b32_e32 v129, 0, v129, vcc
	v_cndmask_b32_e32 v130, 0, v130, vcc
	v_cndmask_b32_e32 v131, 0, v131, vcc
	v_add_f32_e32 v4, v4, v124
	v_add_f32_e32 v5, v5, v125
	v_add_f32_e32 v6, v6, v126
	v_add_f32_e32 v7, v7, v127
	v_add_f32_e32 v8, v8, v128
	v_add_f32_e32 v9, v9, v129
	v_add_f32_e32 v10, v10, v130
	v_add_f32_e32 v11, v11, v131
	v_cmp_eq_u32_e32 vcc, 0, v104
	v_cndmask_b32_e32 v132, 0, v132, vcc
	v_cndmask_b32_e32 v133, 0, v133, vcc
	v_cndmask_b32_e32 v134, 0, v134, vcc
	v_cndmask_b32_e32 v135, 0, v135, vcc
	v_cndmask_b32_e32 v136, 0, v136, vcc
	v_cndmask_b32_e32 v137, 0, v137, vcc
	v_cndmask_b32_e32 v138, 0, v138, vcc
	v_cndmask_b32_e32 v139, 0, v139, vcc
	v_add_f32_e32 v4, v4, v132
	v_add_f32_e32 v5, v5, v133
	v_add_f32_e32 v6, v6, v134
	v_add_f32_e32 v7, v7, v135
	v_add_f32_e32 v8, v8, v136
	v_add_f32_e32 v9, v9, v137
	v_add_f32_e32 v10, v10, v138
	v_add_f32_e32 v11, v11, v139
	v_cvt_pk_bf16_f32 v166, v4, v5
	v_cvt_pk_bf16_f32 v167, v6, v7
	v_cvt_pk_bf16_f32 v168, v8, v9
	v_cvt_pk_bf16_f32 v169, v10, v11
	s_mov_b64 exec, -1
	global_store_dwordx4 v122, v[166:169], s[24:25] offset:1024
	s_nop 1
	s_mov_b32 exec_lo, -1
	s_mov_b32 exec_hi, 0
	v_mov_b32_e32 v100, v2
	v_lshrrev_b32_e32 v102, 4, v100
	v_and_b32_e32 v118, 7, v100
	v_lshlrev_b32_e32 v118, 3, v118
	v_cmp_ne_u32_e32 vcc, 0, v102
	v_cndmask_b32_e32 v106, v140, v142, vcc
	v_lshl_add_u32 v120, v102, 6, v118
	v_mul_u32_u24_e32 v120, 0x108, v120
	v_lshl_add_u32 v110, v106, 3, v120
	v_add_u32_e32 v110, 0x10000, v110
	v_lshlrev_b32_e32 v112, 2, v118
	v_add_u32_e32 v112, s41, v112
	ds_read_b64 v[20:21], v110
	ds_read_b64 v[98:99], v110 offset:264
	ds_read_b64 v[116:117], v110 offset:528
	ds_read_b64 v[148:149], v110 offset:792
	ds_read_b64 v[150:151], v110 offset:1056
	ds_read_b64 v[152:153], v110 offset:1320
	ds_read_b64 v[154:155], v110 offset:1584
	ds_read_b64 v[164:165], v110 offset:1848
	v_lshlrev_b32_e32 v112, 2, v118
	s_lshl_b32 s36, s41, 2
	v_add_u32_e32 v112, s36, v112
	v_add_u32_e32 v112, 0x1ca00, v112
	ds_read_b128 v[12:15], v112
	ds_read_b128 v[16:19], v112 offset:16
	ds_read_b128 v[124:127], v112 offset:4096
	ds_read_b128 v[128:131], v112 offset:4112
	v_bfe_u32 v108, v100, 3, 1
	s_waitcnt lgkmcnt(0)
	v_cmp_ne_u32_e32 vcc, 0, v108
	v_mul_f32_e32 v170, v12, v20
	v_mul_f32_e32 v171, v124, v21
	v_mul_f32_e32 v172, v12, v21
	v_mul_f32_e32 v173, v124, v20
	v_sub_f32_e32 v170, v170, v171
	v_add_f32_e32 v172, v172, v173
	v_xor_b32_e32 v172, 0x80000000, v172
	v_cndmask_b32_e32 v4, v170, v172, vcc
	v_mul_f32_e32 v170, v13, v98
	v_mul_f32_e32 v171, v125, v99
	v_mul_f32_e32 v172, v13, v99
	v_mul_f32_e32 v173, v125, v98
	v_sub_f32_e32 v170, v170, v171
	v_add_f32_e32 v172, v172, v173
	v_xor_b32_e32 v172, 0x80000000, v172
	v_cndmask_b32_e32 v5, v170, v172, vcc
	v_mul_f32_e32 v170, v14, v116
	v_mul_f32_e32 v171, v126, v117
	v_mul_f32_e32 v172, v14, v117
	v_mul_f32_e32 v173, v126, v116
	v_sub_f32_e32 v170, v170, v171
	v_add_f32_e32 v172, v172, v173
	v_xor_b32_e32 v172, 0x80000000, v172
	v_cndmask_b32_e32 v6, v170, v172, vcc
	v_mul_f32_e32 v170, v15, v148
	v_mul_f32_e32 v171, v127, v149
	v_mul_f32_e32 v172, v15, v149
	v_mul_f32_e32 v173, v127, v148
	v_sub_f32_e32 v170, v170, v171
	v_add_f32_e32 v172, v172, v173
	v_xor_b32_e32 v172, 0x80000000, v172
	v_cndmask_b32_e32 v7, v170, v172, vcc
	v_mul_f32_e32 v170, v16, v150
	v_mul_f32_e32 v171, v128, v151
	v_mul_f32_e32 v172, v16, v151
	v_mul_f32_e32 v173, v128, v150
	v_sub_f32_e32 v170, v170, v171
	v_add_f32_e32 v172, v172, v173
	v_xor_b32_e32 v172, 0x80000000, v172
	v_cndmask_b32_e32 v8, v170, v172, vcc
	v_mul_f32_e32 v170, v17, v152
	v_mul_f32_e32 v171, v129, v153
	v_mul_f32_e32 v172, v17, v153
	v_mul_f32_e32 v173, v129, v152
	v_sub_f32_e32 v170, v170, v171
	v_add_f32_e32 v172, v172, v173
	v_xor_b32_e32 v172, 0x80000000, v172
	v_cndmask_b32_e32 v9, v170, v172, vcc
	v_mul_f32_e32 v170, v18, v154
	v_mul_f32_e32 v171, v130, v155
	v_mul_f32_e32 v172, v18, v155
	v_mul_f32_e32 v173, v130, v154
	v_sub_f32_e32 v170, v170, v171
	v_add_f32_e32 v172, v172, v173
	v_xor_b32_e32 v172, 0x80000000, v172
	v_cndmask_b32_e32 v10, v170, v172, vcc
	v_mul_f32_e32 v170, v19, v164
	v_mul_f32_e32 v171, v131, v165
	v_mul_f32_e32 v172, v19, v165
	v_mul_f32_e32 v173, v131, v164
	v_sub_f32_e32 v170, v170, v171
	v_add_f32_e32 v172, v172, v173
	v_xor_b32_e32 v172, 0x80000000, v172
	v_cndmask_b32_e32 v11, v170, v172, vcc
	v_cvt_pk_bf16_f32 v166, v4, v5
	v_cvt_pk_bf16_f32 v167, v6, v7
	v_cvt_pk_bf16_f32 v168, v8, v9
	v_cvt_pk_bf16_f32 v169, v10, v11
	s_mov_b32 exec_lo, 0
	s_mov_b32 exec_hi, -1
	v_add_u32_e32 v100, 0xffffffe0, v2
	v_lshrrev_b32_e32 v102, 1, v100
	v_sub_u32_e32 v104, s0, v102
	v_max_i32_e32 v106, 0, v104
	v_sub_u32_e32 v108, 0, v104
	v_max_i32_e32 v108, 0, v108
	v_and_b32_e32 v118, 1, v100
	v_lshlrev_b32_e32 v118, 5, v118
	v_add_u32_e32 v118, s41, v118
	v_add_u32_e32 v118, 0x1c0, v118
	v_lshl_add_u32 v110, v106, 10, v118
	v_lshl_add_u32 v112, v108, 10, v118
	v_add_u32_e32 v112, 0x8000, v112
	v_add_u32_e32 v114, 0x1e400, v118
	ds_read_b128 v[12:15], v110
	ds_read_b128 v[16:19], v110 offset:16
	ds_read_b128 v[124:127], v112
	ds_read_b128 v[128:131], v112 offset:16
	ds_read_b128 v[132:135], v114
	ds_read_b128 v[136:139], v114 offset:16
	s_waitcnt lgkmcnt(0)
	v_cmp_le_i32_e32 vcc, 0, v104
	v_cndmask_b32_e32 v4, 0, v12, vcc
	v_cndmask_b32_e32 v5, 0, v13, vcc
	v_cndmask_b32_e32 v6, 0, v14, vcc
	v_cndmask_b32_e32 v7, 0, v15, vcc
	v_cndmask_b32_e32 v8, 0, v16, vcc
	v_cndmask_b32_e32 v9, 0, v17, vcc
	v_cndmask_b32_e32 v10, 0, v18, vcc
	v_cndmask_b32_e32 v11, 0, v19, vcc
	v_cmp_ge_i32_e32 vcc, 0, v104
	v_cndmask_b32_e32 v124, 0, v124, vcc
	v_cndmask_b32_e32 v125, 0, v125, vcc
	v_cndmask_b32_e32 v126, 0, v126, vcc
	v_cndmask_b32_e32 v127, 0, v127, vcc
	v_cndmask_b32_e32 v128, 0, v128, vcc
	v_cndmask_b32_e32 v129, 0, v129, vcc
	v_cndmask_b32_e32 v130, 0, v130, vcc
	v_cndmask_b32_e32 v131, 0, v131, vcc
	v_add_f32_e32 v4, v4, v124
	v_add_f32_e32 v5, v5, v125
	v_add_f32_e32 v6, v6, v126
	v_add_f32_e32 v7, v7, v127
	v_add_f32_e32 v8, v8, v128
	v_add_f32_e32 v9, v9, v129
	v_add_f32_e32 v10, v10, v130
	v_add_f32_e32 v11, v11, v131
	v_cmp_eq_u32_e32 vcc, 0, v104
	v_cndmask_b32_e32 v132, 0, v132, vcc
	v_cndmask_b32_e32 v133, 0, v133, vcc
	v_cndmask_b32_e32 v134, 0, v134, vcc
	v_cndmask_b32_e32 v135, 0, v135, vcc
	v_cndmask_b32_e32 v136, 0, v136, vcc
	v_cndmask_b32_e32 v137, 0, v137, vcc
	v_cndmask_b32_e32 v138, 0, v138, vcc
	v_cndmask_b32_e32 v139, 0, v139, vcc
	v_add_f32_e32 v4, v4, v132
	v_add_f32_e32 v5, v5, v133
	v_add_f32_e32 v6, v6, v134
	v_add_f32_e32 v7, v7, v135
	v_add_f32_e32 v8, v8, v136
	v_add_f32_e32 v9, v9, v137
	v_add_f32_e32 v10, v10, v138
	v_add_f32_e32 v11, v11, v139
	v_cvt_pk_bf16_f32 v166, v4, v5
	v_cvt_pk_bf16_f32 v167, v6, v7
	v_cvt_pk_bf16_f32 v168, v8, v9
	v_cvt_pk_bf16_f32 v169, v10, v11
	s_mov_b64 exec, -1
	global_store_dwordx4 v122, v[166:169], s[24:25] offset:2048
	s_nop 1
	s_mov_b32 exec_lo, -1
	s_mov_b32 exec_hi, 0
	v_add_u32_e32 v100, 32, v2
	v_lshrrev_b32_e32 v102, 1, v100
	v_sub_u32_e32 v104, s0, v102
	v_max_i32_e32 v106, 0, v104
	v_sub_u32_e32 v108, 0, v104
	v_max_i32_e32 v108, 0, v108
	v_and_b32_e32 v118, 1, v100
	v_lshlrev_b32_e32 v118, 5, v118
	v_add_u32_e32 v118, s41, v118
	v_add_u32_e32 v118, 0x1c0, v118
	v_lshl_add_u32 v110, v106, 10, v118
	v_lshl_add_u32 v112, v108, 10, v118
	v_add_u32_e32 v112, 0x8000, v112
	v_add_u32_e32 v114, 0x1e400, v118
	ds_read_b128 v[12:15], v110
	ds_read_b128 v[16:19], v110 offset:16
	ds_read_b128 v[124:127], v112
	ds_read_b128 v[128:131], v112 offset:16
	ds_read_b128 v[132:135], v114
	ds_read_b128 v[136:139], v114 offset:16
	s_waitcnt lgkmcnt(0)
	v_cmp_le_i32_e32 vcc, 0, v104
	v_cndmask_b32_e32 v4, 0, v12, vcc
	v_cndmask_b32_e32 v5, 0, v13, vcc
	v_cndmask_b32_e32 v6, 0, v14, vcc
	v_cndmask_b32_e32 v7, 0, v15, vcc
	v_cndmask_b32_e32 v8, 0, v16, vcc
	v_cndmask_b32_e32 v9, 0, v17, vcc
	v_cndmask_b32_e32 v10, 0, v18, vcc
	v_cndmask_b32_e32 v11, 0, v19, vcc
	v_cmp_ge_i32_e32 vcc, 0, v104
	v_cndmask_b32_e32 v124, 0, v124, vcc
	v_cndmask_b32_e32 v125, 0, v125, vcc
	v_cndmask_b32_e32 v126, 0, v126, vcc
	v_cndmask_b32_e32 v127, 0, v127, vcc
	v_cndmask_b32_e32 v128, 0, v128, vcc
	v_cndmask_b32_e32 v129, 0, v129, vcc
	v_cndmask_b32_e32 v130, 0, v130, vcc
	v_cndmask_b32_e32 v131, 0, v131, vcc
	v_add_f32_e32 v4, v4, v124
	v_add_f32_e32 v5, v5, v125
	v_add_f32_e32 v6, v6, v126
	v_add_f32_e32 v7, v7, v127
	v_add_f32_e32 v8, v8, v128
	v_add_f32_e32 v9, v9, v129
	v_add_f32_e32 v10, v10, v130
	v_add_f32_e32 v11, v11, v131
	v_cmp_eq_u32_e32 vcc, 0, v104
	v_cndmask_b32_e32 v132, 0, v132, vcc
	v_cndmask_b32_e32 v133, 0, v133, vcc
	v_cndmask_b32_e32 v134, 0, v134, vcc
	v_cndmask_b32_e32 v135, 0, v135, vcc
	v_cndmask_b32_e32 v136, 0, v136, vcc
	v_cndmask_b32_e32 v137, 0, v137, vcc
	v_cndmask_b32_e32 v138, 0, v138, vcc
	v_cndmask_b32_e32 v139, 0, v139, vcc
	v_add_f32_e32 v4, v4, v132
	v_add_f32_e32 v5, v5, v133
	v_add_f32_e32 v6, v6, v134
	v_add_f32_e32 v7, v7, v135
	v_add_f32_e32 v8, v8, v136
	v_add_f32_e32 v9, v9, v137
	v_add_f32_e32 v10, v10, v138
	v_add_f32_e32 v11, v11, v139
	v_cvt_pk_bf16_f32 v166, v4, v5
	v_cvt_pk_bf16_f32 v167, v6, v7
	v_cvt_pk_bf16_f32 v168, v8, v9
	v_cvt_pk_bf16_f32 v169, v10, v11
	s_mov_b32 exec_lo, 0
	s_mov_b32 exec_hi, -1
	v_subrev_u32_e32 v100, 32, v2
	v_lshrrev_b32_e32 v102, 4, v100
	v_and_b32_e32 v118, 7, v100
	v_lshlrev_b32_e32 v118, 3, v118
	v_cmp_ne_u32_e32 vcc, 0, v102
	v_cndmask_b32_e32 v106, v140, v142, vcc
	v_lshl_add_u32 v120, v102, 6, v118
	v_mul_u32_u24_e32 v120, 0x108, v120
	v_lshl_add_u32 v110, v106, 3, v120
	v_add_u32_e32 v110, 0x10000, v110
	v_lshlrev_b32_e32 v112, 2, v118
	v_add_u32_e32 v112, s41, v112
	ds_read_b64 v[20:21], v110
	ds_read_b64 v[98:99], v110 offset:264
	ds_read_b64 v[116:117], v110 offset:528
	ds_read_b64 v[148:149], v110 offset:792
	ds_read_b64 v[150:151], v110 offset:1056
	ds_read_b64 v[152:153], v110 offset:1320
	ds_read_b64 v[154:155], v110 offset:1584
	ds_read_b64 v[164:165], v110 offset:1848
	v_lshlrev_b32_e32 v112, 2, v118
	s_lshl_b32 s36, s41, 2
	v_add_u32_e32 v112, s36, v112
	v_add_u32_e32 v112, 0x1cb00, v112
	ds_read_b128 v[12:15], v112
	ds_read_b128 v[16:19], v112 offset:16
	ds_read_b128 v[124:127], v112 offset:4096
	ds_read_b128 v[128:131], v112 offset:4112
	v_bfe_u32 v108, v100, 3, 1
	s_waitcnt lgkmcnt(0)
	v_cmp_ne_u32_e32 vcc, 0, v108
	v_mul_f32_e32 v170, v12, v20
	v_mul_f32_e32 v171, v124, v21
	v_mul_f32_e32 v172, v12, v21
	v_mul_f32_e32 v173, v124, v20
	v_sub_f32_e32 v170, v170, v171
	v_add_f32_e32 v172, v172, v173
	v_xor_b32_e32 v172, 0x80000000, v172
	v_cndmask_b32_e32 v4, v170, v172, vcc
	v_mul_f32_e32 v170, v13, v98
	v_mul_f32_e32 v171, v125, v99
	v_mul_f32_e32 v172, v13, v99
	v_mul_f32_e32 v173, v125, v98
	v_sub_f32_e32 v170, v170, v171
	v_add_f32_e32 v172, v172, v173
	v_xor_b32_e32 v172, 0x80000000, v172
	v_cndmask_b32_e32 v5, v170, v172, vcc
	v_mul_f32_e32 v170, v14, v116
	v_mul_f32_e32 v171, v126, v117
	v_mul_f32_e32 v172, v14, v117
	v_mul_f32_e32 v173, v126, v116
	v_sub_f32_e32 v170, v170, v171
	v_add_f32_e32 v172, v172, v173
	v_xor_b32_e32 v172, 0x80000000, v172
	v_cndmask_b32_e32 v6, v170, v172, vcc
	v_mul_f32_e32 v170, v15, v148
	v_mul_f32_e32 v171, v127, v149
	v_mul_f32_e32 v172, v15, v149
	v_mul_f32_e32 v173, v127, v148
	v_sub_f32_e32 v170, v170, v171
	v_add_f32_e32 v172, v172, v173
	v_xor_b32_e32 v172, 0x80000000, v172
	v_cndmask_b32_e32 v7, v170, v172, vcc
	v_mul_f32_e32 v170, v16, v150
	v_mul_f32_e32 v171, v128, v151
	v_mul_f32_e32 v172, v16, v151
	v_mul_f32_e32 v173, v128, v150
	v_sub_f32_e32 v170, v170, v171
	v_add_f32_e32 v172, v172, v173
	v_xor_b32_e32 v172, 0x80000000, v172
	v_cndmask_b32_e32 v8, v170, v172, vcc
	v_mul_f32_e32 v170, v17, v152
	v_mul_f32_e32 v171, v129, v153
	v_mul_f32_e32 v172, v17, v153
	v_mul_f32_e32 v173, v129, v152
	v_sub_f32_e32 v170, v170, v171
	v_add_f32_e32 v172, v172, v173
	v_xor_b32_e32 v172, 0x80000000, v172
	v_cndmask_b32_e32 v9, v170, v172, vcc
	v_mul_f32_e32 v170, v18, v154
	v_mul_f32_e32 v171, v130, v155
	v_mul_f32_e32 v172, v18, v155
	v_mul_f32_e32 v173, v130, v154
	v_sub_f32_e32 v170, v170, v171
	v_add_f32_e32 v172, v172, v173
	v_xor_b32_e32 v172, 0x80000000, v172
	v_cndmask_b32_e32 v10, v170, v172, vcc
	v_mul_f32_e32 v170, v19, v164
	v_mul_f32_e32 v171, v131, v165
	v_mul_f32_e32 v172, v19, v165
	v_mul_f32_e32 v173, v131, v164
	v_sub_f32_e32 v170, v170, v171
	v_add_f32_e32 v172, v172, v173
	v_xor_b32_e32 v172, 0x80000000, v172
	v_cndmask_b32_e32 v11, v170, v172, vcc
	v_cvt_pk_bf16_f32 v166, v4, v5
	v_cvt_pk_bf16_f32 v167, v6, v7
	v_cvt_pk_bf16_f32 v168, v8, v9
	v_cvt_pk_bf16_f32 v169, v10, v11
	s_mov_b64 exec, -1
	global_store_dwordx4 v122, v[166:169], s[24:25] offset:3072
	s_nop 1
	s_lshl_b32 s38, s30, 5
	s_lshl_b32 s36, s31, 2
	s_add_u32 s38, s38, s36
	s_lshl_b32 s36, s29, 8
	s_add_u32 s36, s36, s38
	s_lshl_b32 s36, s36, 10
	s_add_u32 s26, s26, s36
	s_addc_u32 s27, s27, 0
	v_lshrrev_b32_e32 v102, 1, v2
	v_sub_u32_e32 v106, 31, v102
	v_and_b32_e32 v118, 1, v2
	v_lshlrev_b32_e32 v118, 6, v118
	s_lshr_b32 s39, s38, 7
	s_bfe_u32 s40, s38, 0x10006
	s_and_b32 s41, s38, 63
	s_lshl_b32 s36, s39, 6
	s_add_u32 s36, s36, s41
	s_cmp_eq_u32 s39, 0
	s_cselect_b64 vcc, -1, 0
	v_cndmask_b32_e32 v108, v102, v106, vcc
	s_mul_i32 s5, s36, 0x108
	s_add_u32 s5, s5, 0x10000
	v_lshl_add_u32 v110, v108, 3, s5
	s_lshl_b32 s5, s36, 7
	s_add_u32 s5, s5, 0x18400
	v_add_u32_e32 v112, s5, v118
	ds_read_b64 v[20:21], v110
	ds_read_b128 v[12:15], v112
	ds_read_b128 v[16:19], v112 offset:16
	ds_read_b128 v[124:127], v112 offset:32
	ds_read_b128 v[128:131], v112 offset:48
	s_waitcnt lgkmcnt(0)
	s_cmp_eq_u32 s40, 0
	s_cbranch_scc0 .Lp0c_w0
	v_mul_f32_e32 v170, v20, v12
	v_mul_f32_e32 v171, v21, v13
	v_sub_f32_e32 v4, v170, v171
	v_mul_f32_e32 v170, v20, v14
	v_mul_f32_e32 v171, v21, v15
	v_sub_f32_e32 v5, v170, v171
	v_mul_f32_e32 v170, v20, v16
	v_mul_f32_e32 v171, v21, v17
	v_sub_f32_e32 v6, v170, v171
	v_mul_f32_e32 v170, v20, v18
	v_mul_f32_e32 v171, v21, v19
	v_sub_f32_e32 v7, v170, v171
	v_mul_f32_e32 v170, v20, v124
	v_mul_f32_e32 v171, v21, v125
	v_sub_f32_e32 v8, v170, v171
	v_mul_f32_e32 v170, v20, v126
	v_mul_f32_e32 v171, v21, v127
	v_sub_f32_e32 v9, v170, v171
	v_mul_f32_e32 v170, v20, v128
	v_mul_f32_e32 v171, v21, v129
	v_sub_f32_e32 v10, v170, v171
	v_mul_f32_e32 v170, v20, v130
	v_mul_f32_e32 v171, v21, v131
	v_sub_f32_e32 v11, v170, v171
	s_branch .Lp0c_x0
.Lp0c_w0:
	v_mul_f32_e32 v170, v20, v13
	v_mul_f32_e32 v171, v21, v12
	v_add_f32_e32 v4, v171, v170
	v_mul_f32_e32 v170, v20, v15
	v_mul_f32_e32 v171, v21, v14
	v_add_f32_e32 v5, v171, v170
	v_mul_f32_e32 v170, v20, v17
	v_mul_f32_e32 v171, v21, v16
	v_add_f32_e32 v6, v171, v170
	v_mul_f32_e32 v170, v20, v19
	v_mul_f32_e32 v171, v21, v18
	v_add_f32_e32 v7, v171, v170
	v_mul_f32_e32 v170, v20, v125
	v_mul_f32_e32 v171, v21, v124
	v_add_f32_e32 v8, v171, v170
	v_mul_f32_e32 v170, v20, v127
	v_mul_f32_e32 v171, v21, v126
	v_add_f32_e32 v9, v171, v170
	v_mul_f32_e32 v170, v20, v129
	v_mul_f32_e32 v171, v21, v128
	v_add_f32_e32 v10, v171, v170
	v_mul_f32_e32 v170, v20, v131
	v_mul_f32_e32 v171, v21, v130
	v_add_f32_e32 v11, v171, v170
.Lp0c_x0:
	v_cvt_pk_bf16_f32 v166, v4, v5
	v_cvt_pk_bf16_f32 v167, v6, v7
	v_cvt_pk_bf16_f32 v168, v8, v9
	v_cvt_pk_bf16_f32 v169, v10, v11
	global_store_dwordx4 v3, v[166:169], s[26:27]
	s_nop 1
	s_add_u32 s38, s38, 1
	s_lshr_b32 s39, s38, 7
	s_bfe_u32 s40, s38, 0x10006
	s_and_b32 s41, s38, 63
	s_lshl_b32 s36, s39, 6
	s_add_u32 s36, s36, s41
	s_cmp_eq_u32 s39, 0
	s_cselect_b64 vcc, -1, 0
	v_cndmask_b32_e32 v108, v102, v106, vcc
	s_mul_i32 s5, s36, 0x108
	s_add_u32 s5, s5, 0x10000
	v_lshl_add_u32 v110, v108, 3, s5
	s_lshl_b32 s5, s36, 7
	s_add_u32 s5, s5, 0x18400
	v_add_u32_e32 v112, s5, v118
	ds_read_b64 v[20:21], v110
	ds_read_b128 v[12:15], v112
	ds_read_b128 v[16:19], v112 offset:16
	ds_read_b128 v[124:127], v112 offset:32
	ds_read_b128 v[128:131], v112 offset:48
	s_waitcnt lgkmcnt(0)
	s_cmp_eq_u32 s40, 0
	s_cbranch_scc0 .Lp0c_w1
	v_mul_f32_e32 v170, v20, v12
	v_mul_f32_e32 v171, v21, v13
	v_sub_f32_e32 v4, v170, v171
	v_mul_f32_e32 v170, v20, v14
	v_mul_f32_e32 v171, v21, v15
	v_sub_f32_e32 v5, v170, v171
	v_mul_f32_e32 v170, v20, v16
	v_mul_f32_e32 v171, v21, v17
	v_sub_f32_e32 v6, v170, v171
	v_mul_f32_e32 v170, v20, v18
	v_mul_f32_e32 v171, v21, v19
	v_sub_f32_e32 v7, v170, v171
	v_mul_f32_e32 v170, v20, v124
	v_mul_f32_e32 v171, v21, v125
	v_sub_f32_e32 v8, v170, v171
	v_mul_f32_e32 v170, v20, v126
	v_mul_f32_e32 v171, v21, v127
	v_sub_f32_e32 v9, v170, v171
	v_mul_f32_e32 v170, v20, v128
	v_mul_f32_e32 v171, v21, v129
	v_sub_f32_e32 v10, v170, v171
	v_mul_f32_e32 v170, v20, v130
	v_mul_f32_e32 v171, v21, v131
	v_sub_f32_e32 v11, v170, v171
	s_branch .Lp0c_x1

.Lp0c_x1:
	v_cvt_pk_bf16_f32 v166, v4, v5
	v_cvt_pk_bf16_f32 v167, v6, v7
	v_cvt_pk_bf16_f32 v168, v8, v9
	v_cvt_pk_bf16_f32 v169, v10, v11
	global_store_dwordx4 v3, v[166:169], s[26:27] offset:1024
	s_nop 1
	s_add_u32 s38, s38, 1
	s_lshr_b32 s39, s38, 7
	s_bfe_u32 s40, s38, 0x10006
	s_and_b32 s41, s38, 63
	s_lshl_b32 s36, s39, 6
	s_add_u32 s36, s36, s41
	s_cmp_eq_u32 s39, 0
	s_cselect_b64 vcc, -1, 0
	v_cndmask_b32_e32 v108, v102, v106, vcc
	s_mul_i32 s5, s36, 0x108
	s_add_u32 s5, s5, 0x10000
	v_lshl_add_u32 v110, v108, 3, s5
	s_lshl_b32 s5, s36, 7
	s_add_u32 s5, s5, 0x18400
	v_add_u32_e32 v112, s5, v118
	ds_read_b64 v[20:21], v110
	ds_read_b128 v[12:15], v112
	ds_read_b128 v[16:19], v112 offset:16
	ds_read_b128 v[124:127], v112 offset:32
	ds_read_b128 v[128:131], v112 offset:48
	s_waitcnt lgkmcnt(0)
	s_cmp_eq_u32 s40, 0
	s_cbranch_scc0 .Lp0c_w2
	v_mul_f32_e32 v170, v20, v12
	v_mul_f32_e32 v171, v21, v13
	v_sub_f32_e32 v4, v170, v171
	v_mul_f32_e32 v170, v20, v14
	v_mul_f32_e32 v171, v21, v15
	v_sub_f32_e32 v5, v170, v171
	v_mul_f32_e32 v170, v20, v16
	v_mul_f32_e32 v171, v21, v17
	v_sub_f32_e32 v6, v170, v171
	v_mul_f32_e32 v170, v20, v18
	v_mul_f32_e32 v171, v21, v19
	v_sub_f32_e32 v7, v170, v171
	v_mul_f32_e32 v170, v20, v124
	v_mul_f32_e32 v171, v21, v125
	v_sub_f32_e32 v8, v170, v171
	v_mul_f32_e32 v170, v20, v126
	v_mul_f32_e32 v171, v21, v127
	v_sub_f32_e32 v9, v170, v171
	v_mul_f32_e32 v170, v20, v128
	v_mul_f32_e32 v171, v21, v129
	v_sub_f32_e32 v10, v170, v171
	v_mul_f32_e32 v170, v20, v130
	v_mul_f32_e32 v171, v21, v131
	v_sub_f32_e32 v11, v170, v171
	s_branch .Lp0c_x2

.Lp0c_x2:
	v_cvt_pk_bf16_f32 v166, v4, v5
	v_cvt_pk_bf16_f32 v167, v6, v7
	v_cvt_pk_bf16_f32 v168, v8, v9
	v_cvt_pk_bf16_f32 v169, v10, v11
	global_store_dwordx4 v3, v[166:169], s[26:27] offset:2048
	s_nop 1
	s_add_u32 s38, s38, 1
	s_lshr_b32 s39, s38, 7
	s_bfe_u32 s40, s38, 0x10006
	s_and_b32 s41, s38, 63
	s_lshl_b32 s36, s39, 6
	s_add_u32 s36, s36, s41
	s_cmp_eq_u32 s39, 0
	s_cselect_b64 vcc, -1, 0
	v_cndmask_b32_e32 v108, v102, v106, vcc
	s_mul_i32 s5, s36, 0x108
	s_add_u32 s5, s5, 0x10000
	v_lshl_add_u32 v110, v108, 3, s5
	s_lshl_b32 s5, s36, 7
	s_add_u32 s5, s5, 0x18400
	v_add_u32_e32 v112, s5, v118
	ds_read_b64 v[20:21], v110
	ds_read_b128 v[12:15], v112
	ds_read_b128 v[16:19], v112 offset:16
	ds_read_b128 v[124:127], v112 offset:32
	ds_read_b128 v[128:131], v112 offset:48
	s_waitcnt lgkmcnt(0)
	s_cmp_eq_u32 s40, 0
	s_cbranch_scc0 .Lp0c_w3
	v_mul_f32_e32 v170, v20, v12
	v_mul_f32_e32 v171, v21, v13
	v_sub_f32_e32 v4, v170, v171
	v_mul_f32_e32 v170, v20, v14
	v_mul_f32_e32 v171, v21, v15
	v_sub_f32_e32 v5, v170, v171
	v_mul_f32_e32 v170, v20, v16
	v_mul_f32_e32 v171, v21, v17
	v_sub_f32_e32 v6, v170, v171
	v_mul_f32_e32 v170, v20, v18
	v_mul_f32_e32 v171, v21, v19
	v_sub_f32_e32 v7, v170, v171
	v_mul_f32_e32 v170, v20, v124
	v_mul_f32_e32 v171, v21, v125
	v_sub_f32_e32 v8, v170, v171
	v_mul_f32_e32 v170, v20, v126
	v_mul_f32_e32 v171, v21, v127
	v_sub_f32_e32 v9, v170, v171
	v_mul_f32_e32 v170, v20, v128
	v_mul_f32_e32 v171, v21, v129
	v_sub_f32_e32 v10, v170, v171
	v_mul_f32_e32 v170, v20, v130
	v_mul_f32_e32 v171, v21, v131
	v_sub_f32_e32 v11, v170, v171
	s_branch .Lp0c_x3

.Lp0c_x3:
	v_cvt_pk_bf16_f32 v166, v4, v5
	v_cvt_pk_bf16_f32 v167, v6, v7
	v_cvt_pk_bf16_f32 v168, v8, v9
	v_cvt_pk_bf16_f32 v169, v10, v11
	global_store_dwordx4 v3, v[166:169], s[26:27] offset:3072
	s_nop 1
	s_waitcnt lgkmcnt(0)
	s_barrier
	s_mov_b64 s[0:1], s[78:79]
	s_load_dwordx2 s[0:1], s[0:1], 0x100
	s_mov_b64 s[4:5], s[78:79]
	s_load_dwordx2 s[4:5], s[4:5], 0x100
	s_mov_b64 s[18:19], s[78:79]
	s_waitcnt lgkmcnt(0)
	s_add_u32 s36, s0, 0x85b4000
	s_addc_u32 s37, s1, 0
	s_mov_b64 s[0:1], s[78:79]
	s_add_u32 s38, s4, s60
	s_load_dwordx2 s[18:19], s[18:19], 0x100
	s_load_dwordx2 s[20:21], s[0:1], 0x100
	s_addc_u32 s39, s5, 0
	v_readlane_b32 s4, v252, 8
	v_readlane_b32 s5, v252, 9
	v_mov_b32_e32 v8, v224
	s_andn2_b64 vcc, exec, s[4:5]
	v_cndmask_b32_e64 v0, 0, 1, s[4:5]
	v_cmp_ne_u32_e64 s[0:1], 1, v0
	v_readfirstlane_b32 s40, v8
	s_cbranch_vccnz .LBB0_502
	v_readlane_b32 s4, v252, 60
	v_readlane_b32 s5, v252, 61
	s_add_u32 s4, s36, s4
	s_addc_u32 s5, s37, s5
	v_readlane_b32 s22, v253, 0
	v_readlane_b32 s23, v253, 1
	s_add_u32 s30, s38, s22
	s_addc_u32 s31, s39, s23
	v_readlane_b32 s22, v252, 62
	v_readlane_b32 s23, v252, 63
	s_mov_b32 s49, s22
	v_readlane_b32 s22, v252, 58
	s_mov_b32 s50, s22
	v_readlane_b32 s23, v252, 59
